# gate epilogue regenerated stage-major (8 independent chains, v_sqrt_f32) + scan1 inner loop software-pipelined (24 rows prefetch ring)
# speedup vs baseline: 1.0032x; 1.0006x over previous
.LBB0_466:
	s_add_u32 s57, s44, s56
	s_addc_u32 s67, s45, 0
	s_add_u32 s60, s57, 0x100
	s_addc_u32 s61, s67, 0
	s_and_b64 s[58:59], s[54:55], exec
	s_cselect_b32 s61, s31, s61
	s_cselect_b32 s60, s88, s60
	s_add_u32 s56, s8, s56
	s_addc_u32 s58, s9, 0
	s_add_u32 s56, s56, 0x100
	s_addc_u32 s58, s58, 0
	s_and_b64 s[54:55], s[54:55], exec
	s_cselect_b32 s63, s29, s58
	s_cselect_b32 s62, s89, s56
	s_add_u32 s66, s57, 0x100080
	s_addc_u32 s67, s67, 0
	s_add_i32 vcc_hi, s85, s73
	s_add_i32 m0, s4, 0xc000
	s_add_i32 s75, s4, 0xe000
	s_add_i32 vcc_lo, vcc_hi, 0x2000
	s_add_u32 s58, s62, 0x10000
	s_addc_u32 s59, s63, 0
	s_add_i32 s97, s86, s73
	ds_read_b128 v[40:43], v189
	ds_read_b128 v[44:47], v189 offset:1024
	ds_read_b128 v[48:51], v189 offset:2048
	ds_read_b128 v[60:63], v189 offset:3072
	s_add_i32 s96, s97, 0x2000
	s_add_i32 s95, 0, 0x18000
	s_add_u32 s56, s60, 0x100000
	s_addc_u32 s57, s61, 0
	s_add_i32 s94, s95, s73
	s_add_i32 s93, 0, 0x1c000
	s_add_i32 s92, s94, 0x2000
	s_add_u32 s54, s62, 0x10080
	s_addc_u32 s55, s63, 0
	s_add_i32 s91, s93, s73
	s_add_i32 s90, s91, 0x2000
	v_lshl_add_u64 v[176:177], s[66:67], 0, v[180:181]
	ds_read_b128 v[64:67], v212
	ds_read_b128 v[68:71], v212 offset:1024
	ds_read_b128 v[72:75], v212 offset:2048
	ds_read_b128 v[92:95], v212 offset:3072
	ds_read_b128 v[112:115], v212 offset:4096
	ds_read_b128 v[132:135], v212 offset:5120
	ds_read_b128 v[152:155], v212 offset:6144
	ds_read_b128 v[172:175], v212 offset:7168
	global_load_lds_dwordx4 v[176:177], off
	v_lshl_add_u64 v[176:177], s[66:67], 0, v[184:185]
	s_mov_b32 m0, s75
	s_nop 0
	global_load_lds_dwordx4 v[176:177], off
	s_waitcnt lgkmcnt(8)
	s_barrier
	s_waitcnt lgkmcnt(0)
	s_setprio 1
	s_waitcnt lgkmcnt(0)
	v_mfma_f32_16x16x32_bf16 v[168:171], v[40:43], v[64:67], v[168:171]
	v_mfma_f32_16x16x32_bf16 v[160:163], v[48:51], v[64:67], v[160:163]
	v_mfma_f32_16x16x32_bf16 v[148:151], v[40:43], v[72:75], v[148:151]
	v_mfma_f32_16x16x32_bf16 v[140:143], v[48:51], v[72:75], v[140:143]
	v_mfma_f32_16x16x32_bf16 v[128:131], v[40:43], v[112:115], v[128:131]
	v_mfma_f32_16x16x32_bf16 v[120:123], v[48:51], v[112:115], v[120:123]
	v_mfma_f32_16x16x32_bf16 v[108:111], v[40:43], v[152:155], v[108:111]
	v_mfma_f32_16x16x32_bf16 v[100:103], v[48:51], v[152:155], v[100:103]
	v_mfma_f32_16x16x32_bf16 v[168:171], v[44:47], v[68:71], v[168:171]
	v_mfma_f32_16x16x32_bf16 v[160:163], v[60:63], v[68:71], v[160:163]
	v_mfma_f32_16x16x32_bf16 v[148:151], v[44:47], v[92:95], v[148:151]
	v_mfma_f32_16x16x32_bf16 v[140:143], v[60:63], v[92:95], v[140:143]
	v_mfma_f32_16x16x32_bf16 v[128:131], v[44:47], v[132:135], v[128:131]
	v_mfma_f32_16x16x32_bf16 v[120:123], v[60:63], v[132:135], v[120:123]
	v_mfma_f32_16x16x32_bf16 v[108:111], v[44:47], v[172:175], v[108:111]
	v_mfma_f32_16x16x32_bf16 v[100:103], v[60:63], v[172:175], v[100:103]
	s_setprio 0
	s_barrier
	s_mov_b32 m0, vcc_hi
	v_lshl_add_u64 v[208:209], s[62:63], 0, v[182:183]
	ds_read_b128 v[176:179], v213
	ds_read_b128 v[204:207], v213 offset:1024
	ds_read_b128 v[216:219], v213 offset:2048
	ds_read_b128 v[220:223], v213 offset:3072
	global_load_lds_dwordx4 v[208:209], off
	v_lshl_add_u64 v[232:233], s[62:63], 0, v[186:187]
	s_mov_b32 m0, vcc_lo
	s_nop 0
	global_load_lds_dwordx4 v[232:233], off
	s_barrier
	s_waitcnt lgkmcnt(0)
	s_setprio 1
	s_waitcnt lgkmcnt(0)
	v_mfma_f32_16x16x32_bf16 v[164:167], v[176:179], v[64:67], v[164:167]
	v_mfma_f32_16x16x32_bf16 v[64:67], v[216:219], v[64:67], v[156:159]
	v_mfma_f32_16x16x32_bf16 v[164:167], v[204:207], v[68:71], v[164:167]
	v_mfma_f32_16x16x32_bf16 v[64:67], v[220:223], v[68:71], v[64:67]
	v_mfma_f32_16x16x32_bf16 v[68:71], v[176:179], v[72:75], v[144:147]
	v_mfma_f32_16x16x32_bf16 v[72:75], v[216:219], v[72:75], v[136:139]
	v_mfma_f32_16x16x32_bf16 v[104:107], v[176:179], v[152:155], v[104:107]
	v_mfma_f32_16x16x32_bf16 v[96:99], v[216:219], v[152:155], v[96:99]
	v_mfma_f32_16x16x32_bf16 v[68:71], v[204:207], v[92:95], v[68:71]
	v_mfma_f32_16x16x32_bf16 v[72:75], v[220:223], v[92:95], v[72:75]
	v_mfma_f32_16x16x32_bf16 v[92:95], v[176:179], v[112:115], v[124:127]
	v_mfma_f32_16x16x32_bf16 v[112:115], v[216:219], v[112:115], v[116:119]
	v_mfma_f32_16x16x32_bf16 v[104:107], v[204:207], v[172:175], v[104:107]
	v_mfma_f32_16x16x32_bf16 v[96:99], v[220:223], v[172:175], v[96:99]
	v_mfma_f32_16x16x32_bf16 v[92:95], v[204:207], v[132:135], v[92:95]
	v_mfma_f32_16x16x32_bf16 v[112:115], v[220:223], v[132:135], v[112:115]
	s_setprio 0
	s_mov_b32 m0, s4
	v_lshl_add_u64 v[234:235], s[60:61], 0, v[180:181]
	s_barrier
	ds_read_b128 v[116:119], v212 offset:16384
	ds_read_b128 v[124:127], v212 offset:17408
	ds_read_b128 v[132:135], v212 offset:18432
	ds_read_b128 v[136:139], v212 offset:19456
	ds_read_b128 v[144:147], v212 offset:20480
	ds_read_b128 v[152:155], v212 offset:21504
	ds_read_b128 v[156:159], v212 offset:22528
	ds_read_b128 v[172:175], v212 offset:23552
	global_load_lds_dwordx4 v[234:235], off
	v_lshl_add_u64 v[236:237], s[60:61], 0, v[184:185]
	s_mov_b32 m0, s78
	s_nop 0
	global_load_lds_dwordx4 v[236:237], off
	s_barrier
	s_waitcnt lgkmcnt(0)
	s_setprio 1
	s_waitcnt lgkmcnt(0)
	v_mfma_f32_16x16x32_bf16 v[88:91], v[40:43], v[116:119], v[88:91]
	v_mfma_f32_16x16x32_bf16 v[80:83], v[48:51], v[116:119], v[80:83]
	v_mfma_f32_16x16x32_bf16 v[56:59], v[40:43], v[132:135], v[56:59]
	v_mfma_f32_16x16x32_bf16 v[36:39], v[48:51], v[132:135], v[36:39]
	v_mfma_f32_16x16x32_bf16 v[28:31], v[40:43], v[144:147], v[28:31]
	v_mfma_f32_16x16x32_bf16 v[20:23], v[48:51], v[144:147], v[20:23]
	v_mfma_f32_16x16x32_bf16 v[12:15], v[40:43], v[156:159], v[12:15]
	v_mfma_f32_16x16x32_bf16 v[4:7], v[48:51], v[156:159], v[4:7]
	v_mfma_f32_16x16x32_bf16 v[88:91], v[44:47], v[124:127], v[88:91]
	v_mfma_f32_16x16x32_bf16 v[80:83], v[60:63], v[124:127], v[80:83]
	v_mfma_f32_16x16x32_bf16 v[56:59], v[44:47], v[136:139], v[56:59]
	v_mfma_f32_16x16x32_bf16 v[36:39], v[60:63], v[136:139], v[36:39]
	v_mfma_f32_16x16x32_bf16 v[28:31], v[44:47], v[152:155], v[28:31]
	v_mfma_f32_16x16x32_bf16 v[20:23], v[60:63], v[152:155], v[20:23]
	v_mfma_f32_16x16x32_bf16 v[12:15], v[44:47], v[172:175], v[12:15]
	v_mfma_f32_16x16x32_bf16 v[4:7], v[60:63], v[172:175], v[4:7]
	s_setprio 0
	s_barrier
	s_mov_b32 m0, s97
	v_lshl_add_u64 v[40:41], s[58:59], 0, v[182:183]
	global_load_lds_dwordx4 v[40:41], off
	v_lshl_add_u64 v[40:41], s[58:59], 0, v[186:187]
	s_mov_b32 m0, s96
	s_nop 0
	global_load_lds_dwordx4 v[40:41], off
	s_waitcnt vmcnt(6)
	s_barrier
	s_setprio 1
	v_mfma_f32_16x16x32_bf16 v[32:35], v[216:219], v[132:135], v[32:35]
	v_mfma_f32_16x16x32_bf16 v[24:27], v[176:179], v[144:147], v[24:27]
	v_mfma_f32_16x16x32_bf16 v[16:19], v[216:219], v[144:147], v[16:19]
	v_mfma_f32_16x16x32_bf16 v[8:11], v[176:179], v[156:159], v[8:11]
	v_mfma_f32_16x16x32_bf16 v[0:3], v[216:219], v[156:159], v[0:3]
	v_mfma_f32_16x16x32_bf16 v[40:43], v[176:179], v[116:119], v[84:87]
	v_mfma_f32_16x16x32_bf16 v[44:47], v[216:219], v[116:119], v[76:79]
	v_mfma_f32_16x16x32_bf16 v[48:51], v[176:179], v[132:135], v[52:55]
	v_mfma_f32_16x16x32_bf16 v[32:35], v[220:223], v[136:139], v[32:35]
	v_mfma_f32_16x16x32_bf16 v[24:27], v[204:207], v[152:155], v[24:27]
	v_mfma_f32_16x16x32_bf16 v[16:19], v[220:223], v[152:155], v[16:19]
	v_mfma_f32_16x16x32_bf16 v[8:11], v[204:207], v[172:175], v[8:11]
	v_mfma_f32_16x16x32_bf16 v[0:3], v[220:223], v[172:175], v[0:3]
	v_mfma_f32_16x16x32_bf16 v[40:43], v[204:207], v[124:127], v[40:43]
	v_mfma_f32_16x16x32_bf16 v[44:47], v[220:223], v[124:127], v[44:47]
	v_mfma_f32_16x16x32_bf16 v[48:51], v[204:207], v[136:139], v[48:51]
	s_setprio 0
	v_add_u32_e32 v84, s95, v211
	s_barrier
	ds_read_b128 v[52:55], v84
	ds_read_b128 v[60:63], v84 offset:1024
	ds_read_b128 v[76:79], v84 offset:2048
	ds_read_b128 v[84:87], v84 offset:3072
	s_mov_b32 m0, s79
	v_lshl_add_u64 v[144:145], s[56:57], 0, v[180:181]
	ds_read_b128 v[116:119], v212 offset:32768
	ds_read_b128 v[124:127], v212 offset:33792
	ds_read_b128 v[132:135], v212 offset:34816
	ds_read_b128 v[136:139], v212 offset:35840
	ds_read_b128 v[152:155], v212 offset:36864
	ds_read_b128 v[172:175], v212 offset:37888
	ds_read_b128 v[176:179], v212 offset:38912
	ds_read_b128 v[204:207], v212 offset:39936
	global_load_lds_dwordx4 v[144:145], off
	v_lshl_add_u64 v[144:145], s[56:57], 0, v[184:185]
	s_mov_b32 m0, s81
	s_nop 0
	global_load_lds_dwordx4 v[144:145], off
	s_waitcnt lgkmcnt(8)
	s_barrier
	s_waitcnt lgkmcnt(0)
	s_setprio 1
	s_waitcnt lgkmcnt(0)
	v_mfma_f32_16x16x32_bf16 v[144:147], v[52:55], v[116:119], v[168:171]
	v_mfma_f32_16x16x32_bf16 v[168:171], v[60:63], v[124:127], v[144:147]
	v_mfma_f32_16x16x32_bf16 v[144:147], v[76:79], v[116:119], v[160:163]
	v_mfma_f32_16x16x32_bf16 v[160:163], v[84:87], v[124:127], v[144:147]
	v_mfma_f32_16x16x32_bf16 v[144:147], v[52:55], v[132:135], v[148:151]
	v_mfma_f32_16x16x32_bf16 v[140:143], v[76:79], v[132:135], v[140:143]
	v_mfma_f32_16x16x32_bf16 v[128:131], v[52:55], v[152:155], v[128:131]
	v_mfma_f32_16x16x32_bf16 v[120:123], v[76:79], v[152:155], v[120:123]
	v_mfma_f32_16x16x32_bf16 v[108:111], v[52:55], v[176:179], v[108:111]
	v_mfma_f32_16x16x32_bf16 v[100:103], v[76:79], v[176:179], v[100:103]
	v_mfma_f32_16x16x32_bf16 v[148:151], v[60:63], v[136:139], v[144:147]
	v_mfma_f32_16x16x32_bf16 v[140:143], v[84:87], v[136:139], v[140:143]
	v_mfma_f32_16x16x32_bf16 v[128:131], v[60:63], v[172:175], v[128:131]
	v_mfma_f32_16x16x32_bf16 v[120:123], v[84:87], v[172:175], v[120:123]
	v_mfma_f32_16x16x32_bf16 v[108:111], v[60:63], v[204:207], v[108:111]
	v_mfma_f32_16x16x32_bf16 v[100:103], v[84:87], v[204:207], v[100:103]
	s_setprio 0
	s_barrier
	v_add_u32_e32 v144, s93, v211
	s_mov_b32 m0, s94
	ds_read_b128 v[216:219], v144
	ds_read_b128 v[220:223], v144 offset:1024
	ds_read_b128 v[224:227], v144 offset:2048
	ds_read_b128 v[228:231], v144 offset:3072
	v_lshl_add_u64 v[144:145], v[208:209], 0, s[22:23]
	global_load_lds_dwordx4 v[144:145], off
	v_lshl_add_u64 v[144:145], v[232:233], 0, s[22:23]
	s_mov_b32 m0, s92
	s_nop 0
	global_load_lds_dwordx4 v[144:145], off
	s_barrier
	s_waitcnt lgkmcnt(0)
	s_setprio 1
	s_waitcnt lgkmcnt(0)
	v_mfma_f32_16x16x32_bf16 v[64:67], v[224:227], v[116:119], v[64:67]
	v_mfma_f32_16x16x32_bf16 v[144:147], v[216:219], v[116:119], v[164:167]
	v_mfma_f32_16x16x32_bf16 v[156:159], v[228:231], v[124:127], v[64:67]
	v_mfma_f32_16x16x32_bf16 v[64:67], v[216:219], v[132:135], v[68:71]
	v_mfma_f32_16x16x32_bf16 v[164:167], v[220:223], v[124:127], v[144:147]
	v_mfma_f32_16x16x32_bf16 v[144:147], v[220:223], v[136:139], v[64:67]
	v_mfma_f32_16x16x32_bf16 v[64:67], v[224:227], v[132:135], v[72:75]
	v_mfma_f32_16x16x32_bf16 v[136:139], v[228:231], v[136:139], v[64:67]
	v_mfma_f32_16x16x32_bf16 v[64:67], v[216:219], v[152:155], v[92:95]
	v_mfma_f32_16x16x32_bf16 v[124:127], v[220:223], v[172:175], v[64:67]
	v_mfma_f32_16x16x32_bf16 v[64:67], v[224:227], v[152:155], v[112:115]
	v_mfma_f32_16x16x32_bf16 v[116:119], v[228:231], v[172:175], v[64:67]
	v_mfma_f32_16x16x32_bf16 v[64:67], v[216:219], v[176:179], v[104:107]
	v_mfma_f32_16x16x32_bf16 v[104:107], v[220:223], v[204:207], v[64:67]
	v_mfma_f32_16x16x32_bf16 v[64:67], v[224:227], v[176:179], v[96:99]
	v_mfma_f32_16x16x32_bf16 v[96:99], v[228:231], v[204:207], v[64:67]
	s_setprio 0
	s_mov_b32 m0, s83
	v_lshl_add_u64 v[176:177], v[234:235], 0, s[22:23]
	s_barrier
	s_nop 2
	ds_read_b128 v[64:67], v212 offset:49152
	ds_read_b128 v[68:71], v212 offset:50176
	ds_read_b128 v[72:75], v212 offset:51200
	ds_read_b128 v[92:95], v212 offset:52224
	ds_read_b128 v[112:115], v212 offset:53248
	ds_read_b128 v[132:135], v212 offset:54272
	ds_read_b128 v[152:155], v212 offset:55296
	ds_read_b128 v[172:175], v212 offset:56320
	global_load_lds_dwordx4 v[176:177], off
	v_lshl_add_u64 v[176:177], v[236:237], 0, s[22:23]
	s_mov_b32 m0, s84
	s_nop 0
	global_load_lds_dwordx4 v[176:177], off
	s_barrier
	s_waitcnt lgkmcnt(0)
	s_setprio 1
	s_waitcnt lgkmcnt(0)
	v_mfma_f32_16x16x32_bf16 v[88:91], v[52:55], v[64:67], v[88:91]
	v_mfma_f32_16x16x32_bf16 v[80:83], v[76:79], v[64:67], v[80:83]
	v_mfma_f32_16x16x32_bf16 v[56:59], v[52:55], v[72:75], v[56:59]
	v_mfma_f32_16x16x32_bf16 v[36:39], v[76:79], v[72:75], v[36:39]
	v_mfma_f32_16x16x32_bf16 v[28:31], v[52:55], v[112:115], v[28:31]
	v_mfma_f32_16x16x32_bf16 v[20:23], v[76:79], v[112:115], v[20:23]
	v_mfma_f32_16x16x32_bf16 v[12:15], v[52:55], v[152:155], v[12:15]
	v_mfma_f32_16x16x32_bf16 v[4:7], v[76:79], v[152:155], v[4:7]
	v_mfma_f32_16x16x32_bf16 v[88:91], v[60:63], v[68:71], v[88:91]
	v_mfma_f32_16x16x32_bf16 v[80:83], v[84:87], v[68:71], v[80:83]
	v_mfma_f32_16x16x32_bf16 v[56:59], v[60:63], v[92:95], v[56:59]
	v_mfma_f32_16x16x32_bf16 v[36:39], v[84:87], v[92:95], v[36:39]
	v_mfma_f32_16x16x32_bf16 v[28:31], v[60:63], v[132:135], v[28:31]
	v_mfma_f32_16x16x32_bf16 v[20:23], v[84:87], v[132:135], v[20:23]
	v_mfma_f32_16x16x32_bf16 v[12:15], v[60:63], v[172:175], v[12:15]
	v_mfma_f32_16x16x32_bf16 v[4:7], v[84:87], v[172:175], v[4:7]
	s_setprio 0
	s_barrier
	s_mov_b32 m0, s91
	v_lshl_add_u64 v[52:53], s[54:55], 0, v[182:183]
	global_load_lds_dwordx4 v[52:53], off
	v_lshl_add_u64 v[52:53], s[54:55], 0, v[186:187]
	s_mov_b32 m0, s90
	s_nop 0
	global_load_lds_dwordx4 v[52:53], off
	s_waitcnt vmcnt(6)
	s_barrier
	s_setprio 1
	v_mfma_f32_16x16x32_bf16 v[40:43], v[216:219], v[64:67], v[40:43]
	v_mfma_f32_16x16x32_bf16 v[84:87], v[220:223], v[68:71], v[40:43]
	v_mfma_f32_16x16x32_bf16 v[40:43], v[224:227], v[64:67], v[44:47]
	v_mfma_f32_16x16x32_bf16 v[76:79], v[228:231], v[68:71], v[40:43]
	v_mfma_f32_16x16x32_bf16 v[40:43], v[216:219], v[72:75], v[48:51]
	v_mfma_f32_16x16x32_bf16 v[32:35], v[224:227], v[72:75], v[32:35]
	v_mfma_f32_16x16x32_bf16 v[24:27], v[216:219], v[112:115], v[24:27]
	v_mfma_f32_16x16x32_bf16 v[16:19], v[224:227], v[112:115], v[16:19]
	v_mfma_f32_16x16x32_bf16 v[8:11], v[216:219], v[152:155], v[8:11]
	v_mfma_f32_16x16x32_bf16 v[0:3], v[224:227], v[152:155], v[0:3]
	v_mfma_f32_16x16x32_bf16 v[52:55], v[220:223], v[92:95], v[40:43]
	v_mfma_f32_16x16x32_bf16 v[32:35], v[228:231], v[92:95], v[32:35]
	v_mfma_f32_16x16x32_bf16 v[24:27], v[220:223], v[132:135], v[24:27]
	v_mfma_f32_16x16x32_bf16 v[16:19], v[228:231], v[132:135], v[16:19]
	v_mfma_f32_16x16x32_bf16 v[8:11], v[220:223], v[172:175], v[8:11]
	v_mfma_f32_16x16x32_bf16 v[0:3], v[228:231], v[172:175], v[0:3]
	s_setprio 0
	s_movk_i32 s56, 0x100
	s_andn2_b64 vcc, exec, s[48:49]
	s_mov_b64 s[54:55], -1
	s_mov_b64 s[48:49], 0
	s_barrier
	s_cbranch_vccz .LBB0_466
	v_lshl_or_b32 v40, s1, 7, v190
	v_lshl_add_u32 v72, s0, 8, v188
	v_ashrrev_i32_e32 v41, 31, v40
	v_ashrrev_i32_e32 v73, 31, v72
	v_lshl_add_u64 v[74:75], v[40:41], 1, s[14:15]
	v_lshlrev_b64 v[42:43], 13, v[72:73]
	v_lshl_add_u64 v[42:43], v[74:75], 0, v[42:43]
	v_lshlrev_b64 v[40:41], 2, v[40:41]
	global_load_dwordx4 v[216:219], v[42:43], off nt
	v_lshl_add_u64 v[42:43], s[64:65], 0, v[40:41]
	global_load_dwordx4 v[64:67], v[42:43], off
	v_lshl_add_u64 v[44:45], s[36:37], 0, v[40:41]
	global_load_dwordx4 v[68:71], v[44:45], off
	v_lshl_add_u64 v[40:41], s[16:17], 0, v[40:41]
	global_load_dwordx4 v[60:63], v[40:41], off
	global_load_dwordx4 v[48:51], v[42:43], off offset:16
	s_nop 0
	global_load_dwordx4 v[44:47], v[44:45], off offset:16
	s_nop 0
	global_load_dwordx4 v[40:43], v[40:41], off offset:16
	v_or_b32_e32 v92, 16, v72
	v_or_b32_e32 v94, 32, v72
	v_or_b32_e32 v112, 48, v72
	v_add_u32_e32 v114, 0x80, v72
	v_add_u32_e32 v132, 0x90, v72
	v_add_u32_e32 v134, 0xa0, v72
	v_add_u32_e32 v72, 0xb0, v72
	v_ashrrev_i32_e32 v93, 31, v92
	v_ashrrev_i32_e32 v95, 31, v94
	v_ashrrev_i32_e32 v113, 31, v112
	v_ashrrev_i32_e32 v115, 31, v114
	v_ashrrev_i32_e32 v133, 31, v132
	v_ashrrev_i32_e32 v135, 31, v134
	v_ashrrev_i32_e32 v73, 31, v72
	v_lshlrev_b64 v[92:93], 13, v[92:93]
	v_lshlrev_b64 v[94:95], 13, v[94:95]
	v_lshlrev_b64 v[112:113], 13, v[112:113]
	v_lshlrev_b64 v[114:115], 13, v[114:115]
	v_lshlrev_b64 v[132:133], 13, v[132:133]
	v_lshlrev_b64 v[134:135], 13, v[134:135]
	v_lshlrev_b64 v[72:73], 13, v[72:73]
	v_lshl_add_u64 v[92:93], v[74:75], 0, v[92:93]
	v_lshl_add_u64 v[94:95], v[74:75], 0, v[94:95]
	v_lshl_add_u64 v[112:113], v[74:75], 0, v[112:113]
	v_lshl_add_u64 v[114:115], v[74:75], 0, v[114:115]
	v_lshl_add_u64 v[206:207], v[74:75], 0, v[132:133]
	v_lshl_add_u64 v[208:209], v[74:75], 0, v[134:135]
	v_lshl_add_u64 v[72:73], v[74:75], 0, v[72:73]
	global_load_dwordx4 v[176:179], v[92:93], off nt
	global_load_dwordx4 v[172:175], v[94:95], off nt
	global_load_dwordx4 v[152:155], v[112:113], off nt
	global_load_dwordx4 v[132:135], v[114:115], off nt
	s_nop 0
	global_load_dwordx4 v[112:115], v[206:207], off nt
	global_load_dwordx4 v[92:95], v[208:209], off nt
	s_nop 0
	global_load_dwordx4 v[72:75], v[72:73], off nt
	s_lshl_b32 s0, s0, 6
	s_add_i32 s44, s0, s1
	s_ashr_i32 s45, s44, 31
	s_lshl_b64 s[0:1], s[44:45], 14
	v_mov_b32_e32 v205, s1
	v_or_b32_e32 v204, s0, v190
	s_waitcnt vmcnt(0)
	v_pk_add_f32 v[168:169], v[168:169], v[64:65]
	v_pk_add_f32 v[164:165], v[164:165], v[68:69]
	v_pk_add_f32 v[170:171], v[170:171], v[66:67]
	v_pk_add_f32 v[166:167], v[166:167], v[70:71]
	v_pk_add_f32 v[160:161], v[160:161], v[48:49]
	v_pk_add_f32 v[156:157], v[156:157], v[44:45]
	v_pk_add_f32 v[162:163], v[162:163], v[50:51]
	v_pk_add_f32 v[158:159], v[158:159], v[46:47]
	v_pk_add_f32 v[148:149], v[148:149], v[64:65]
	v_pk_add_f32 v[144:145], v[144:145], v[68:69]
	v_pk_add_f32 v[150:151], v[150:151], v[66:67]
	v_pk_add_f32 v[146:147], v[146:147], v[70:71]
	v_pk_add_f32 v[140:141], v[140:141], v[48:49]
	v_pk_add_f32 v[136:137], v[136:137], v[44:45]
	v_pk_add_f32 v[142:143], v[142:143], v[50:51]
	v_pk_add_f32 v[138:139], v[138:139], v[46:47]
	v_pk_mul_f32 v[168:169], v[168:169], s[24:25] op_sel_hi:[1,0]
	v_pk_mul_f32 v[164:165], v[164:165], s[24:25] op_sel_hi:[1,0]
	v_pk_mul_f32 v[170:171], v[170:171], s[24:25] op_sel_hi:[1,0]
	v_pk_mul_f32 v[166:167], v[166:167], s[24:25] op_sel_hi:[1,0]
	v_pk_mul_f32 v[160:161], v[160:161], s[24:25] op_sel_hi:[1,0]
	v_pk_mul_f32 v[156:157], v[156:157], s[24:25] op_sel_hi:[1,0]
	v_pk_mul_f32 v[162:163], v[162:163], s[24:25] op_sel_hi:[1,0]
	v_pk_mul_f32 v[158:159], v[158:159], s[24:25] op_sel_hi:[1,0]
	v_pk_mul_f32 v[148:149], v[148:149], s[24:25] op_sel_hi:[1,0]
	v_pk_mul_f32 v[144:145], v[144:145], s[24:25] op_sel_hi:[1,0]
	v_pk_mul_f32 v[150:151], v[150:151], s[24:25] op_sel_hi:[1,0]
	v_pk_mul_f32 v[146:147], v[146:147], s[24:25] op_sel_hi:[1,0]
	v_pk_mul_f32 v[140:141], v[140:141], s[24:25] op_sel_hi:[1,0]
	v_pk_mul_f32 v[136:137], v[136:137], s[24:25] op_sel_hi:[1,0]
	v_pk_mul_f32 v[142:143], v[142:143], s[24:25] op_sel_hi:[1,0]
	v_pk_mul_f32 v[138:139], v[138:139], s[24:25] op_sel_hi:[1,0]
	v_exp_f32_e32 v168, v168
	v_exp_f32_e32 v169, v169
	v_exp_f32_e32 v164, v164
	v_exp_f32_e32 v165, v165
	v_exp_f32_e32 v170, v170
	v_exp_f32_e32 v171, v171
	v_exp_f32_e32 v166, v166
	v_exp_f32_e32 v167, v167
	v_exp_f32_e32 v160, v160
	v_exp_f32_e32 v161, v161
	v_exp_f32_e32 v156, v156
	v_exp_f32_e32 v157, v157
	v_exp_f32_e32 v162, v162
	v_exp_f32_e32 v163, v163
	v_exp_f32_e32 v158, v158
	v_exp_f32_e32 v159, v159
	v_exp_f32_e32 v148, v148
	v_exp_f32_e32 v149, v149
	v_exp_f32_e32 v144, v144
	v_exp_f32_e32 v145, v145
	v_exp_f32_e32 v150, v150
	v_exp_f32_e32 v151, v151
	v_exp_f32_e32 v146, v146
	v_exp_f32_e32 v147, v147
	v_exp_f32_e32 v140, v140
	v_exp_f32_e32 v141, v141
	v_exp_f32_e32 v136, v136
	v_exp_f32_e32 v137, v137
	v_exp_f32_e32 v142, v142
	v_exp_f32_e32 v143, v143
	v_exp_f32_e32 v138, v138
	v_exp_f32_e32 v139, v139
	v_pk_add_f32 v[168:169], v[168:169], 1.0 op_sel_hi:[1,0]
	v_pk_add_f32 v[164:165], v[164:165], 1.0 op_sel_hi:[1,0]
	v_pk_add_f32 v[170:171], v[170:171], 1.0 op_sel_hi:[1,0]
	v_pk_add_f32 v[166:167], v[166:167], 1.0 op_sel_hi:[1,0]
	v_pk_add_f32 v[160:161], v[160:161], 1.0 op_sel_hi:[1,0]
	v_pk_add_f32 v[156:157], v[156:157], 1.0 op_sel_hi:[1,0]
	v_pk_add_f32 v[162:163], v[162:163], 1.0 op_sel_hi:[1,0]
	v_pk_add_f32 v[158:159], v[158:159], 1.0 op_sel_hi:[1,0]
	v_pk_add_f32 v[148:149], v[148:149], 1.0 op_sel_hi:[1,0]
	v_pk_add_f32 v[144:145], v[144:145], 1.0 op_sel_hi:[1,0]
	v_pk_add_f32 v[150:151], v[150:151], 1.0 op_sel_hi:[1,0]
	v_pk_add_f32 v[146:147], v[146:147], 1.0 op_sel_hi:[1,0]
	v_pk_add_f32 v[140:141], v[140:141], 1.0 op_sel_hi:[1,0]
	v_pk_add_f32 v[136:137], v[136:137], 1.0 op_sel_hi:[1,0]
	v_pk_add_f32 v[142:143], v[142:143], 1.0 op_sel_hi:[1,0]
	v_pk_add_f32 v[138:139], v[138:139], 1.0 op_sel_hi:[1,0]
	v_rcp_f32_e32 v168, v168
	v_rcp_f32_e32 v169, v169
	v_rcp_f32_e32 v164, v164
	v_rcp_f32_e32 v165, v165
	v_rcp_f32_e32 v170, v170
	v_rcp_f32_e32 v171, v171
	v_rcp_f32_e32 v166, v166
	v_rcp_f32_e32 v167, v167
	v_rcp_f32_e32 v160, v160
	v_rcp_f32_e32 v161, v161
	v_rcp_f32_e32 v156, v156
	v_rcp_f32_e32 v157, v157
	v_rcp_f32_e32 v162, v162
	v_rcp_f32_e32 v163, v163
	v_rcp_f32_e32 v158, v158
	v_rcp_f32_e32 v159, v159
	v_rcp_f32_e32 v148, v148
	v_rcp_f32_e32 v149, v149
	v_rcp_f32_e32 v144, v144
	v_rcp_f32_e32 v145, v145
	v_rcp_f32_e32 v150, v150
	v_rcp_f32_e32 v151, v151
	v_rcp_f32_e32 v146, v146
	v_rcp_f32_e32 v147, v147
	v_rcp_f32_e32 v140, v140
	v_rcp_f32_e32 v141, v141
	v_rcp_f32_e32 v136, v136
	v_rcp_f32_e32 v137, v137
	v_rcp_f32_e32 v142, v142
	v_rcp_f32_e32 v143, v143
	v_rcp_f32_e32 v138, v138
	v_rcp_f32_e32 v139, v139
	v_pk_mul_f32 v[168:169], v[60:61], v[168:169] neg_lo:[1,0] neg_hi:[1,0]
	v_pk_mul_f32 v[170:171], v[62:63], v[170:171] neg_lo:[1,0] neg_hi:[1,0]
	v_pk_mul_f32 v[160:161], v[40:41], v[160:161] neg_lo:[1,0] neg_hi:[1,0]
	v_pk_mul_f32 v[162:163], v[42:43], v[162:163] neg_lo:[1,0] neg_hi:[1,0]
	v_pk_mul_f32 v[148:149], v[60:61], v[148:149] neg_lo:[1,0] neg_hi:[1,0]
	v_pk_mul_f32 v[150:151], v[62:63], v[150:151] neg_lo:[1,0] neg_hi:[1,0]
	v_pk_mul_f32 v[140:141], v[40:41], v[140:141] neg_lo:[1,0] neg_hi:[1,0]
	v_pk_mul_f32 v[142:143], v[42:43], v[142:143] neg_lo:[1,0] neg_hi:[1,0]
	v_pk_mul_f32 v[220:221], v[168:169], s[26:27] op_sel_hi:[1,0]
	v_pk_mul_f32 v[222:223], v[170:171], s[26:27] op_sel_hi:[1,0]
	v_pk_mul_f32 v[224:225], v[160:161], s[26:27] op_sel_hi:[1,0]
	v_pk_mul_f32 v[226:227], v[162:163], s[26:27] op_sel_hi:[1,0]
	v_pk_mul_f32 v[228:229], v[148:149], s[26:27] op_sel_hi:[1,0]
	v_pk_mul_f32 v[230:231], v[150:151], s[26:27] op_sel_hi:[1,0]
	v_pk_mul_f32 v[232:233], v[140:141], s[26:27] op_sel_hi:[1,0]
	v_pk_mul_f32 v[234:235], v[142:143], s[26:27] op_sel_hi:[1,0]
	v_exp_f32_e32 v220, v220
	v_exp_f32_e32 v221, v221
	v_exp_f32_e32 v222, v222
	v_exp_f32_e32 v223, v223
	v_exp_f32_e32 v224, v224
	v_exp_f32_e32 v225, v225
	v_exp_f32_e32 v226, v226
	v_exp_f32_e32 v227, v227
	v_exp_f32_e32 v228, v228
	v_exp_f32_e32 v229, v229
	v_exp_f32_e32 v230, v230
	v_exp_f32_e32 v231, v231
	v_exp_f32_e32 v232, v232
	v_exp_f32_e32 v233, v233
	v_exp_f32_e32 v234, v234
	v_exp_f32_e32 v235, v235
	v_pk_add_f32 v[220:221], v[220:221], 1.0 op_sel_hi:[1,0] neg_lo:[1,0] neg_hi:[1,0]
	v_pk_add_f32 v[222:223], v[222:223], 1.0 op_sel_hi:[1,0] neg_lo:[1,0] neg_hi:[1,0]
	v_pk_add_f32 v[224:225], v[224:225], 1.0 op_sel_hi:[1,0] neg_lo:[1,0] neg_hi:[1,0]
	v_pk_add_f32 v[226:227], v[226:227], 1.0 op_sel_hi:[1,0] neg_lo:[1,0] neg_hi:[1,0]
	v_pk_add_f32 v[228:229], v[228:229], 1.0 op_sel_hi:[1,0] neg_lo:[1,0] neg_hi:[1,0]
	v_pk_add_f32 v[230:231], v[230:231], 1.0 op_sel_hi:[1,0] neg_lo:[1,0] neg_hi:[1,0]
	v_pk_add_f32 v[232:233], v[232:233], 1.0 op_sel_hi:[1,0] neg_lo:[1,0] neg_hi:[1,0]
	v_pk_add_f32 v[234:235], v[234:235], 1.0 op_sel_hi:[1,0] neg_lo:[1,0] neg_hi:[1,0]
	v_max_f32_e32 v220, 0, v220
	v_max_f32_e32 v221, 0, v221
	v_max_f32_e32 v222, 0, v222
	v_max_f32_e32 v223, 0, v223
	v_max_f32_e32 v224, 0, v224
	v_max_f32_e32 v225, 0, v225
	v_max_f32_e32 v226, 0, v226
	v_max_f32_e32 v227, 0, v227
	v_max_f32_e32 v228, 0, v228
	v_max_f32_e32 v229, 0, v229
	v_max_f32_e32 v230, 0, v230
	v_max_f32_e32 v231, 0, v231
	v_max_f32_e32 v232, 0, v232
	v_max_f32_e32 v233, 0, v233
	v_max_f32_e32 v234, 0, v234
	v_max_f32_e32 v235, 0, v235
	v_sqrt_f32_e32 v220, v220
	v_sqrt_f32_e32 v221, v221
	v_sqrt_f32_e32 v222, v222
	v_sqrt_f32_e32 v223, v223
	v_sqrt_f32_e32 v224, v224
	v_sqrt_f32_e32 v225, v225
	v_sqrt_f32_e32 v226, v226
	v_sqrt_f32_e32 v227, v227
	v_sqrt_f32_e32 v228, v228
	v_sqrt_f32_e32 v229, v229
	v_sqrt_f32_e32 v230, v230
	v_sqrt_f32_e32 v231, v231
	v_sqrt_f32_e32 v232, v232
	v_sqrt_f32_e32 v233, v233
	v_sqrt_f32_e32 v234, v234
	v_sqrt_f32_e32 v235, v235
	v_pk_mul_f32 v[164:165], v[164:165], v[220:221]
	v_pk_mul_f32 v[166:167], v[166:167], v[222:223]
	v_pk_mul_f32 v[156:157], v[156:157], v[224:225]
	v_pk_mul_f32 v[158:159], v[158:159], v[226:227]
	v_pk_mul_f32 v[144:145], v[144:145], v[228:229]
	v_pk_mul_f32 v[146:147], v[146:147], v[230:231]
	v_pk_mul_f32 v[136:137], v[136:137], v[232:233]
	v_pk_mul_f32 v[138:139], v[138:139], v[234:235]
	v_lshlrev_b32_e32 v220, 16, v216
	v_and_b32_e32 v221, 0xffff0000, v216
	v_lshlrev_b32_e32 v222, 16, v217
	v_and_b32_e32 v223, 0xffff0000, v217
	v_lshlrev_b32_e32 v224, 16, v218
	v_and_b32_e32 v225, 0xffff0000, v218
	v_lshlrev_b32_e32 v226, 16, v219
	v_and_b32_e32 v227, 0xffff0000, v219
	v_lshlrev_b32_e32 v228, 16, v176
	v_and_b32_e32 v229, 0xffff0000, v176
	v_lshlrev_b32_e32 v230, 16, v177
	v_and_b32_e32 v231, 0xffff0000, v177
	v_lshlrev_b32_e32 v232, 16, v178
	v_and_b32_e32 v233, 0xffff0000, v178
	v_lshlrev_b32_e32 v234, 16, v179
	v_and_b32_e32 v235, 0xffff0000, v179
	v_pk_mul_f32 v[164:165], v[164:165], v[220:221]
	v_pk_mul_f32 v[166:167], v[166:167], v[222:223]
	v_pk_mul_f32 v[156:157], v[156:157], v[224:225]
	v_pk_mul_f32 v[158:159], v[158:159], v[226:227]
	v_pk_mul_f32 v[144:145], v[144:145], v[228:229]
	v_pk_mul_f32 v[146:147], v[146:147], v[230:231]
	v_pk_mul_f32 v[136:137], v[136:137], v[232:233]
	v_pk_mul_f32 v[138:139], v[138:139], v[234:235]
	v_cvt_pk_bf16_f32 v220, v168, v169
	v_cvt_pk_bf16_f32 v221, v170, v171
	v_cvt_pk_bf16_f32 v222, v160, v161
	v_cvt_pk_bf16_f32 v223, v162, v163
	v_cvt_pk_bf16_f32 v228, v148, v149
	v_cvt_pk_bf16_f32 v229, v150, v151
	v_cvt_pk_bf16_f32 v230, v140, v141
	v_cvt_pk_bf16_f32 v231, v142, v143
	v_cvt_pk_bf16_f32 v224, v164, v165
	v_cvt_pk_bf16_f32 v225, v166, v167
	v_cvt_pk_bf16_f32 v226, v156, v157
	v_cvt_pk_bf16_f32 v227, v158, v159
	v_cvt_pk_bf16_f32 v232, v144, v145
	v_cvt_pk_bf16_f32 v233, v146, v147
	v_cvt_pk_bf16_f32 v234, v136, v137
	v_cvt_pk_bf16_f32 v235, v138, v139
	v_lshl_add_u64 v[206:207], v[204:205], 0, v[192:193]
	v_lshlrev_b64 v[206:207], 1, v[206:207]
	v_lshl_add_u64 v[208:209], s[18:19], 0, v[206:207]
	v_lshl_add_u64 v[236:237], s[20:21], 0, v[206:207]
	global_store_dwordx4 v[208:209], v[220:223], off
	global_store_dwordx4 v[236:237], v[224:227], off
	v_lshl_add_u64 v[206:207], v[204:205], 0, v[194:195]
	v_lshlrev_b64 v[206:207], 1, v[206:207]
	v_lshl_add_u64 v[208:209], s[18:19], 0, v[206:207]
	v_lshl_add_u64 v[236:237], s[20:21], 0, v[206:207]
	global_store_dwordx4 v[208:209], v[228:231], off
	global_store_dwordx4 v[236:237], v[232:235], off
	v_pk_add_f32 v[128:129], v[128:129], v[64:65]
	v_pk_add_f32 v[124:125], v[124:125], v[68:69]
	v_pk_add_f32 v[130:131], v[130:131], v[66:67]
	v_pk_add_f32 v[126:127], v[126:127], v[70:71]
	v_pk_add_f32 v[120:121], v[120:121], v[48:49]
	v_pk_add_f32 v[116:117], v[116:117], v[44:45]
	v_pk_add_f32 v[122:123], v[122:123], v[50:51]
	v_pk_add_f32 v[118:119], v[118:119], v[46:47]
	v_pk_add_f32 v[108:109], v[108:109], v[64:65]
	v_pk_add_f32 v[104:105], v[104:105], v[68:69]
	v_pk_add_f32 v[110:111], v[110:111], v[66:67]
	v_pk_add_f32 v[106:107], v[106:107], v[70:71]
	v_pk_add_f32 v[100:101], v[100:101], v[48:49]
	v_pk_add_f32 v[96:97], v[96:97], v[44:45]
	v_pk_add_f32 v[102:103], v[102:103], v[50:51]
	v_pk_add_f32 v[98:99], v[98:99], v[46:47]
	v_pk_mul_f32 v[128:129], v[128:129], s[24:25] op_sel_hi:[1,0]
	v_pk_mul_f32 v[124:125], v[124:125], s[24:25] op_sel_hi:[1,0]
	v_pk_mul_f32 v[130:131], v[130:131], s[24:25] op_sel_hi:[1,0]
	v_pk_mul_f32 v[126:127], v[126:127], s[24:25] op_sel_hi:[1,0]
	v_pk_mul_f32 v[120:121], v[120:121], s[24:25] op_sel_hi:[1,0]
	v_pk_mul_f32 v[116:117], v[116:117], s[24:25] op_sel_hi:[1,0]
	v_pk_mul_f32 v[122:123], v[122:123], s[24:25] op_sel_hi:[1,0]
	v_pk_mul_f32 v[118:119], v[118:119], s[24:25] op_sel_hi:[1,0]
	v_pk_mul_f32 v[108:109], v[108:109], s[24:25] op_sel_hi:[1,0]
	v_pk_mul_f32 v[104:105], v[104:105], s[24:25] op_sel_hi:[1,0]
	v_pk_mul_f32 v[110:111], v[110:111], s[24:25] op_sel_hi:[1,0]
	v_pk_mul_f32 v[106:107], v[106:107], s[24:25] op_sel_hi:[1,0]
	v_pk_mul_f32 v[100:101], v[100:101], s[24:25] op_sel_hi:[1,0]
	v_pk_mul_f32 v[96:97], v[96:97], s[24:25] op_sel_hi:[1,0]
	v_pk_mul_f32 v[102:103], v[102:103], s[24:25] op_sel_hi:[1,0]
	v_pk_mul_f32 v[98:99], v[98:99], s[24:25] op_sel_hi:[1,0]
	v_exp_f32_e32 v128, v128
	v_exp_f32_e32 v129, v129
	v_exp_f32_e32 v124, v124
	v_exp_f32_e32 v125, v125
	v_exp_f32_e32 v130, v130
	v_exp_f32_e32 v131, v131
	v_exp_f32_e32 v126, v126
	v_exp_f32_e32 v127, v127
	v_exp_f32_e32 v120, v120
	v_exp_f32_e32 v121, v121
	v_exp_f32_e32 v116, v116
	v_exp_f32_e32 v117, v117
	v_exp_f32_e32 v122, v122
	v_exp_f32_e32 v123, v123
	v_exp_f32_e32 v118, v118
	v_exp_f32_e32 v119, v119
	v_exp_f32_e32 v108, v108
	v_exp_f32_e32 v109, v109
	v_exp_f32_e32 v104, v104
	v_exp_f32_e32 v105, v105
	v_exp_f32_e32 v110, v110
	v_exp_f32_e32 v111, v111
	v_exp_f32_e32 v106, v106
	v_exp_f32_e32 v107, v107
	v_exp_f32_e32 v100, v100
	v_exp_f32_e32 v101, v101
	v_exp_f32_e32 v96, v96
	v_exp_f32_e32 v97, v97
	v_exp_f32_e32 v102, v102
	v_exp_f32_e32 v103, v103
	v_exp_f32_e32 v98, v98
	v_exp_f32_e32 v99, v99
	v_pk_add_f32 v[128:129], v[128:129], 1.0 op_sel_hi:[1,0]
	v_pk_add_f32 v[124:125], v[124:125], 1.0 op_sel_hi:[1,0]
	v_pk_add_f32 v[130:131], v[130:131], 1.0 op_sel_hi:[1,0]
	v_pk_add_f32 v[126:127], v[126:127], 1.0 op_sel_hi:[1,0]
	v_pk_add_f32 v[120:121], v[120:121], 1.0 op_sel_hi:[1,0]
	v_pk_add_f32 v[116:117], v[116:117], 1.0 op_sel_hi:[1,0]
	v_pk_add_f32 v[122:123], v[122:123], 1.0 op_sel_hi:[1,0]
	v_pk_add_f32 v[118:119], v[118:119], 1.0 op_sel_hi:[1,0]
	v_pk_add_f32 v[108:109], v[108:109], 1.0 op_sel_hi:[1,0]
	v_pk_add_f32 v[104:105], v[104:105], 1.0 op_sel_hi:[1,0]
	v_pk_add_f32 v[110:111], v[110:111], 1.0 op_sel_hi:[1,0]
	v_pk_add_f32 v[106:107], v[106:107], 1.0 op_sel_hi:[1,0]
	v_pk_add_f32 v[100:101], v[100:101], 1.0 op_sel_hi:[1,0]
	v_pk_add_f32 v[96:97], v[96:97], 1.0 op_sel_hi:[1,0]
	v_pk_add_f32 v[102:103], v[102:103], 1.0 op_sel_hi:[1,0]
	v_pk_add_f32 v[98:99], v[98:99], 1.0 op_sel_hi:[1,0]
	v_rcp_f32_e32 v128, v128
	v_rcp_f32_e32 v129, v129
	v_rcp_f32_e32 v124, v124
	v_rcp_f32_e32 v125, v125
	v_rcp_f32_e32 v130, v130
	v_rcp_f32_e32 v131, v131
	v_rcp_f32_e32 v126, v126
	v_rcp_f32_e32 v127, v127
	v_rcp_f32_e32 v120, v120
	v_rcp_f32_e32 v121, v121
	v_rcp_f32_e32 v116, v116
	v_rcp_f32_e32 v117, v117
	v_rcp_f32_e32 v122, v122
	v_rcp_f32_e32 v123, v123
	v_rcp_f32_e32 v118, v118
	v_rcp_f32_e32 v119, v119
	v_rcp_f32_e32 v108, v108
	v_rcp_f32_e32 v109, v109
	v_rcp_f32_e32 v104, v104
	v_rcp_f32_e32 v105, v105
	v_rcp_f32_e32 v110, v110
	v_rcp_f32_e32 v111, v111
	v_rcp_f32_e32 v106, v106
	v_rcp_f32_e32 v107, v107
	v_rcp_f32_e32 v100, v100
	v_rcp_f32_e32 v101, v101
	v_rcp_f32_e32 v96, v96
	v_rcp_f32_e32 v97, v97
	v_rcp_f32_e32 v102, v102
	v_rcp_f32_e32 v103, v103
	v_rcp_f32_e32 v98, v98
	v_rcp_f32_e32 v99, v99
	v_pk_mul_f32 v[128:129], v[60:61], v[128:129] neg_lo:[1,0] neg_hi:[1,0]
	v_pk_mul_f32 v[130:131], v[62:63], v[130:131] neg_lo:[1,0] neg_hi:[1,0]
	v_pk_mul_f32 v[120:121], v[40:41], v[120:121] neg_lo:[1,0] neg_hi:[1,0]
	v_pk_mul_f32 v[122:123], v[42:43], v[122:123] neg_lo:[1,0] neg_hi:[1,0]
	v_pk_mul_f32 v[108:109], v[60:61], v[108:109] neg_lo:[1,0] neg_hi:[1,0]
	v_pk_mul_f32 v[110:111], v[62:63], v[110:111] neg_lo:[1,0] neg_hi:[1,0]
	v_pk_mul_f32 v[100:101], v[40:41], v[100:101] neg_lo:[1,0] neg_hi:[1,0]
	v_pk_mul_f32 v[102:103], v[42:43], v[102:103] neg_lo:[1,0] neg_hi:[1,0]
	v_pk_mul_f32 v[220:221], v[128:129], s[26:27] op_sel_hi:[1,0]
	v_pk_mul_f32 v[222:223], v[130:131], s[26:27] op_sel_hi:[1,0]
	v_pk_mul_f32 v[224:225], v[120:121], s[26:27] op_sel_hi:[1,0]
	v_pk_mul_f32 v[226:227], v[122:123], s[26:27] op_sel_hi:[1,0]
	v_pk_mul_f32 v[228:229], v[108:109], s[26:27] op_sel_hi:[1,0]
	v_pk_mul_f32 v[230:231], v[110:111], s[26:27] op_sel_hi:[1,0]
	v_pk_mul_f32 v[232:233], v[100:101], s[26:27] op_sel_hi:[1,0]
	v_pk_mul_f32 v[234:235], v[102:103], s[26:27] op_sel_hi:[1,0]
	v_exp_f32_e32 v220, v220
	v_exp_f32_e32 v221, v221
	v_exp_f32_e32 v222, v222
	v_exp_f32_e32 v223, v223
	v_exp_f32_e32 v224, v224
	v_exp_f32_e32 v225, v225
	v_exp_f32_e32 v226, v226
	v_exp_f32_e32 v227, v227
	v_exp_f32_e32 v228, v228
	v_exp_f32_e32 v229, v229
	v_exp_f32_e32 v230, v230
	v_exp_f32_e32 v231, v231
	v_exp_f32_e32 v232, v232
	v_exp_f32_e32 v233, v233
	v_exp_f32_e32 v234, v234
	v_exp_f32_e32 v235, v235
	v_pk_add_f32 v[220:221], v[220:221], 1.0 op_sel_hi:[1,0] neg_lo:[1,0] neg_hi:[1,0]
	v_pk_add_f32 v[222:223], v[222:223], 1.0 op_sel_hi:[1,0] neg_lo:[1,0] neg_hi:[1,0]
	v_pk_add_f32 v[224:225], v[224:225], 1.0 op_sel_hi:[1,0] neg_lo:[1,0] neg_hi:[1,0]
	v_pk_add_f32 v[226:227], v[226:227], 1.0 op_sel_hi:[1,0] neg_lo:[1,0] neg_hi:[1,0]
	v_pk_add_f32 v[228:229], v[228:229], 1.0 op_sel_hi:[1,0] neg_lo:[1,0] neg_hi:[1,0]
	v_pk_add_f32 v[230:231], v[230:231], 1.0 op_sel_hi:[1,0] neg_lo:[1,0] neg_hi:[1,0]
	v_pk_add_f32 v[232:233], v[232:233], 1.0 op_sel_hi:[1,0] neg_lo:[1,0] neg_hi:[1,0]
	v_pk_add_f32 v[234:235], v[234:235], 1.0 op_sel_hi:[1,0] neg_lo:[1,0] neg_hi:[1,0]
	v_max_f32_e32 v220, 0, v220
	v_max_f32_e32 v221, 0, v221
	v_max_f32_e32 v222, 0, v222
	v_max_f32_e32 v223, 0, v223
	v_max_f32_e32 v224, 0, v224
	v_max_f32_e32 v225, 0, v225
	v_max_f32_e32 v226, 0, v226
	v_max_f32_e32 v227, 0, v227
	v_max_f32_e32 v228, 0, v228
	v_max_f32_e32 v229, 0, v229
	v_max_f32_e32 v230, 0, v230
	v_max_f32_e32 v231, 0, v231
	v_max_f32_e32 v232, 0, v232
	v_max_f32_e32 v233, 0, v233
	v_max_f32_e32 v234, 0, v234
	v_max_f32_e32 v235, 0, v235
	v_sqrt_f32_e32 v220, v220
	v_sqrt_f32_e32 v221, v221
	v_sqrt_f32_e32 v222, v222
	v_sqrt_f32_e32 v223, v223
	v_sqrt_f32_e32 v224, v224
	v_sqrt_f32_e32 v225, v225
	v_sqrt_f32_e32 v226, v226
	v_sqrt_f32_e32 v227, v227
	v_sqrt_f32_e32 v228, v228
	v_sqrt_f32_e32 v229, v229
	v_sqrt_f32_e32 v230, v230
	v_sqrt_f32_e32 v231, v231
	v_sqrt_f32_e32 v232, v232
	v_sqrt_f32_e32 v233, v233
	v_sqrt_f32_e32 v234, v234
	v_sqrt_f32_e32 v235, v235
	v_pk_mul_f32 v[124:125], v[124:125], v[220:221]
	v_pk_mul_f32 v[126:127], v[126:127], v[222:223]
	v_pk_mul_f32 v[116:117], v[116:117], v[224:225]
	v_pk_mul_f32 v[118:119], v[118:119], v[226:227]
	v_pk_mul_f32 v[104:105], v[104:105], v[228:229]
	v_pk_mul_f32 v[106:107], v[106:107], v[230:231]
	v_pk_mul_f32 v[96:97], v[96:97], v[232:233]
	v_pk_mul_f32 v[98:99], v[98:99], v[234:235]
	v_lshlrev_b32_e32 v220, 16, v172
	v_and_b32_e32 v221, 0xffff0000, v172
	v_lshlrev_b32_e32 v222, 16, v173
	v_and_b32_e32 v223, 0xffff0000, v173
	v_lshlrev_b32_e32 v224, 16, v174
	v_and_b32_e32 v225, 0xffff0000, v174
	v_lshlrev_b32_e32 v226, 16, v175
	v_and_b32_e32 v227, 0xffff0000, v175
	v_lshlrev_b32_e32 v228, 16, v152
	v_and_b32_e32 v229, 0xffff0000, v152
	v_lshlrev_b32_e32 v230, 16, v153
	v_and_b32_e32 v231, 0xffff0000, v153
	v_lshlrev_b32_e32 v232, 16, v154
	v_and_b32_e32 v233, 0xffff0000, v154
	v_lshlrev_b32_e32 v234, 16, v155
	v_and_b32_e32 v235, 0xffff0000, v155
	v_pk_mul_f32 v[124:125], v[124:125], v[220:221]
	v_pk_mul_f32 v[126:127], v[126:127], v[222:223]
	v_pk_mul_f32 v[116:117], v[116:117], v[224:225]
	v_pk_mul_f32 v[118:119], v[118:119], v[226:227]
	v_pk_mul_f32 v[104:105], v[104:105], v[228:229]
	v_pk_mul_f32 v[106:107], v[106:107], v[230:231]
	v_pk_mul_f32 v[96:97], v[96:97], v[232:233]
	v_pk_mul_f32 v[98:99], v[98:99], v[234:235]
	v_cvt_pk_bf16_f32 v220, v128, v129
	v_cvt_pk_bf16_f32 v221, v130, v131
	v_cvt_pk_bf16_f32 v222, v120, v121
	v_cvt_pk_bf16_f32 v223, v122, v123
	v_cvt_pk_bf16_f32 v228, v108, v109
	v_cvt_pk_bf16_f32 v229, v110, v111
	v_cvt_pk_bf16_f32 v230, v100, v101
	v_cvt_pk_bf16_f32 v231, v102, v103
	v_cvt_pk_bf16_f32 v224, v124, v125
	v_cvt_pk_bf16_f32 v225, v126, v127
	v_cvt_pk_bf16_f32 v226, v116, v117
	v_cvt_pk_bf16_f32 v227, v118, v119
	v_cvt_pk_bf16_f32 v232, v104, v105
	v_cvt_pk_bf16_f32 v233, v106, v107
	v_cvt_pk_bf16_f32 v234, v96, v97
	v_cvt_pk_bf16_f32 v235, v98, v99
	v_lshl_add_u64 v[206:207], v[204:205], 0, v[196:197]
	v_lshlrev_b64 v[206:207], 1, v[206:207]
	v_lshl_add_u64 v[208:209], s[18:19], 0, v[206:207]
	v_lshl_add_u64 v[236:237], s[20:21], 0, v[206:207]
	global_store_dwordx4 v[208:209], v[220:223], off
	global_store_dwordx4 v[236:237], v[224:227], off
	v_lshl_add_u64 v[206:207], v[204:205], 0, v[198:199]
	v_lshlrev_b64 v[206:207], 1, v[206:207]
	v_lshl_add_u64 v[208:209], s[18:19], 0, v[206:207]
	v_lshl_add_u64 v[236:237], s[20:21], 0, v[206:207]
	global_store_dwordx4 v[208:209], v[228:231], off
	global_store_dwordx4 v[236:237], v[232:235], off
	v_pk_add_f32 v[88:89], v[88:89], v[64:65]
	v_pk_add_f32 v[84:85], v[84:85], v[68:69]
	v_pk_add_f32 v[90:91], v[90:91], v[66:67]
	v_pk_add_f32 v[86:87], v[86:87], v[70:71]
	v_pk_add_f32 v[80:81], v[80:81], v[48:49]
	v_pk_add_f32 v[76:77], v[76:77], v[44:45]
	v_pk_add_f32 v[82:83], v[82:83], v[50:51]
	v_pk_add_f32 v[78:79], v[78:79], v[46:47]
	v_pk_add_f32 v[56:57], v[56:57], v[64:65]
	v_pk_add_f32 v[52:53], v[52:53], v[68:69]
	v_pk_add_f32 v[58:59], v[58:59], v[66:67]
	v_pk_add_f32 v[54:55], v[54:55], v[70:71]
	v_pk_add_f32 v[36:37], v[36:37], v[48:49]
	v_pk_add_f32 v[32:33], v[32:33], v[44:45]
	v_pk_add_f32 v[38:39], v[38:39], v[50:51]
	v_pk_add_f32 v[34:35], v[34:35], v[46:47]
	v_pk_mul_f32 v[88:89], v[88:89], s[24:25] op_sel_hi:[1,0]
	v_pk_mul_f32 v[84:85], v[84:85], s[24:25] op_sel_hi:[1,0]
	v_pk_mul_f32 v[90:91], v[90:91], s[24:25] op_sel_hi:[1,0]
	v_pk_mul_f32 v[86:87], v[86:87], s[24:25] op_sel_hi:[1,0]
	v_pk_mul_f32 v[80:81], v[80:81], s[24:25] op_sel_hi:[1,0]
	v_pk_mul_f32 v[76:77], v[76:77], s[24:25] op_sel_hi:[1,0]
	v_pk_mul_f32 v[82:83], v[82:83], s[24:25] op_sel_hi:[1,0]
	v_pk_mul_f32 v[78:79], v[78:79], s[24:25] op_sel_hi:[1,0]
	v_pk_mul_f32 v[56:57], v[56:57], s[24:25] op_sel_hi:[1,0]
	v_pk_mul_f32 v[52:53], v[52:53], s[24:25] op_sel_hi:[1,0]
	v_pk_mul_f32 v[58:59], v[58:59], s[24:25] op_sel_hi:[1,0]
	v_pk_mul_f32 v[54:55], v[54:55], s[24:25] op_sel_hi:[1,0]
	v_pk_mul_f32 v[36:37], v[36:37], s[24:25] op_sel_hi:[1,0]
	v_pk_mul_f32 v[32:33], v[32:33], s[24:25] op_sel_hi:[1,0]
	v_pk_mul_f32 v[38:39], v[38:39], s[24:25] op_sel_hi:[1,0]
	v_pk_mul_f32 v[34:35], v[34:35], s[24:25] op_sel_hi:[1,0]
	v_exp_f32_e32 v88, v88
	v_exp_f32_e32 v89, v89
	v_exp_f32_e32 v84, v84
	v_exp_f32_e32 v85, v85
	v_exp_f32_e32 v90, v90
	v_exp_f32_e32 v91, v91
	v_exp_f32_e32 v86, v86
	v_exp_f32_e32 v87, v87
	v_exp_f32_e32 v80, v80
	v_exp_f32_e32 v81, v81
	v_exp_f32_e32 v76, v76
	v_exp_f32_e32 v77, v77
	v_exp_f32_e32 v82, v82
	v_exp_f32_e32 v83, v83
	v_exp_f32_e32 v78, v78
	v_exp_f32_e32 v79, v79
	v_exp_f32_e32 v56, v56
	v_exp_f32_e32 v57, v57
	v_exp_f32_e32 v52, v52
	v_exp_f32_e32 v53, v53
	v_exp_f32_e32 v58, v58
	v_exp_f32_e32 v59, v59
	v_exp_f32_e32 v54, v54
	v_exp_f32_e32 v55, v55
	v_exp_f32_e32 v36, v36
	v_exp_f32_e32 v37, v37
	v_exp_f32_e32 v32, v32
	v_exp_f32_e32 v33, v33
	v_exp_f32_e32 v38, v38
	v_exp_f32_e32 v39, v39
	v_exp_f32_e32 v34, v34
	v_exp_f32_e32 v35, v35
	v_pk_add_f32 v[88:89], v[88:89], 1.0 op_sel_hi:[1,0]
	v_pk_add_f32 v[84:85], v[84:85], 1.0 op_sel_hi:[1,0]
	v_pk_add_f32 v[90:91], v[90:91], 1.0 op_sel_hi:[1,0]
	v_pk_add_f32 v[86:87], v[86:87], 1.0 op_sel_hi:[1,0]
	v_pk_add_f32 v[80:81], v[80:81], 1.0 op_sel_hi:[1,0]
	v_pk_add_f32 v[76:77], v[76:77], 1.0 op_sel_hi:[1,0]
	v_pk_add_f32 v[82:83], v[82:83], 1.0 op_sel_hi:[1,0]
	v_pk_add_f32 v[78:79], v[78:79], 1.0 op_sel_hi:[1,0]
	v_pk_add_f32 v[56:57], v[56:57], 1.0 op_sel_hi:[1,0]
	v_pk_add_f32 v[52:53], v[52:53], 1.0 op_sel_hi:[1,0]
	v_pk_add_f32 v[58:59], v[58:59], 1.0 op_sel_hi:[1,0]
	v_pk_add_f32 v[54:55], v[54:55], 1.0 op_sel_hi:[1,0]
	v_pk_add_f32 v[36:37], v[36:37], 1.0 op_sel_hi:[1,0]
	v_pk_add_f32 v[32:33], v[32:33], 1.0 op_sel_hi:[1,0]
	v_pk_add_f32 v[38:39], v[38:39], 1.0 op_sel_hi:[1,0]
	v_pk_add_f32 v[34:35], v[34:35], 1.0 op_sel_hi:[1,0]
	v_rcp_f32_e32 v88, v88
	v_rcp_f32_e32 v89, v89
	v_rcp_f32_e32 v84, v84
	v_rcp_f32_e32 v85, v85
	v_rcp_f32_e32 v90, v90
	v_rcp_f32_e32 v91, v91
	v_rcp_f32_e32 v86, v86
	v_rcp_f32_e32 v87, v87
	v_rcp_f32_e32 v80, v80
	v_rcp_f32_e32 v81, v81
	v_rcp_f32_e32 v76, v76
	v_rcp_f32_e32 v77, v77
	v_rcp_f32_e32 v82, v82
	v_rcp_f32_e32 v83, v83
	v_rcp_f32_e32 v78, v78
	v_rcp_f32_e32 v79, v79
	v_rcp_f32_e32 v56, v56
	v_rcp_f32_e32 v57, v57
	v_rcp_f32_e32 v52, v52
	v_rcp_f32_e32 v53, v53
	v_rcp_f32_e32 v58, v58
	v_rcp_f32_e32 v59, v59
	v_rcp_f32_e32 v54, v54
	v_rcp_f32_e32 v55, v55
	v_rcp_f32_e32 v36, v36
	v_rcp_f32_e32 v37, v37
	v_rcp_f32_e32 v32, v32
	v_rcp_f32_e32 v33, v33
	v_rcp_f32_e32 v38, v38
	v_rcp_f32_e32 v39, v39
	v_rcp_f32_e32 v34, v34
	v_rcp_f32_e32 v35, v35
	v_pk_mul_f32 v[88:89], v[60:61], v[88:89] neg_lo:[1,0] neg_hi:[1,0]
	v_pk_mul_f32 v[90:91], v[62:63], v[90:91] neg_lo:[1,0] neg_hi:[1,0]
	v_pk_mul_f32 v[80:81], v[40:41], v[80:81] neg_lo:[1,0] neg_hi:[1,0]
	v_pk_mul_f32 v[82:83], v[42:43], v[82:83] neg_lo:[1,0] neg_hi:[1,0]
	v_pk_mul_f32 v[56:57], v[60:61], v[56:57] neg_lo:[1,0] neg_hi:[1,0]
	v_pk_mul_f32 v[58:59], v[62:63], v[58:59] neg_lo:[1,0] neg_hi:[1,0]
	v_pk_mul_f32 v[36:37], v[40:41], v[36:37] neg_lo:[1,0] neg_hi:[1,0]
	v_pk_mul_f32 v[38:39], v[42:43], v[38:39] neg_lo:[1,0] neg_hi:[1,0]
	v_pk_mul_f32 v[220:221], v[88:89], s[26:27] op_sel_hi:[1,0]
	v_pk_mul_f32 v[222:223], v[90:91], s[26:27] op_sel_hi:[1,0]
	v_pk_mul_f32 v[224:225], v[80:81], s[26:27] op_sel_hi:[1,0]
	v_pk_mul_f32 v[226:227], v[82:83], s[26:27] op_sel_hi:[1,0]
	v_pk_mul_f32 v[228:229], v[56:57], s[26:27] op_sel_hi:[1,0]
	v_pk_mul_f32 v[230:231], v[58:59], s[26:27] op_sel_hi:[1,0]
	v_pk_mul_f32 v[232:233], v[36:37], s[26:27] op_sel_hi:[1,0]
	v_pk_mul_f32 v[234:235], v[38:39], s[26:27] op_sel_hi:[1,0]
	v_exp_f32_e32 v220, v220
	v_exp_f32_e32 v221, v221
	v_exp_f32_e32 v222, v222
	v_exp_f32_e32 v223, v223
	v_exp_f32_e32 v224, v224
	v_exp_f32_e32 v225, v225
	v_exp_f32_e32 v226, v226
	v_exp_f32_e32 v227, v227
	v_exp_f32_e32 v228, v228
	v_exp_f32_e32 v229, v229
	v_exp_f32_e32 v230, v230
	v_exp_f32_e32 v231, v231
	v_exp_f32_e32 v232, v232
	v_exp_f32_e32 v233, v233
	v_exp_f32_e32 v234, v234
	v_exp_f32_e32 v235, v235
	v_pk_add_f32 v[220:221], v[220:221], 1.0 op_sel_hi:[1,0] neg_lo:[1,0] neg_hi:[1,0]
	v_pk_add_f32 v[222:223], v[222:223], 1.0 op_sel_hi:[1,0] neg_lo:[1,0] neg_hi:[1,0]
	v_pk_add_f32 v[224:225], v[224:225], 1.0 op_sel_hi:[1,0] neg_lo:[1,0] neg_hi:[1,0]
	v_pk_add_f32 v[226:227], v[226:227], 1.0 op_sel_hi:[1,0] neg_lo:[1,0] neg_hi:[1,0]
	v_pk_add_f32 v[228:229], v[228:229], 1.0 op_sel_hi:[1,0] neg_lo:[1,0] neg_hi:[1,0]
	v_pk_add_f32 v[230:231], v[230:231], 1.0 op_sel_hi:[1,0] neg_lo:[1,0] neg_hi:[1,0]
	v_pk_add_f32 v[232:233], v[232:233], 1.0 op_sel_hi:[1,0] neg_lo:[1,0] neg_hi:[1,0]
	v_pk_add_f32 v[234:235], v[234:235], 1.0 op_sel_hi:[1,0] neg_lo:[1,0] neg_hi:[1,0]
	v_max_f32_e32 v220, 0, v220
	v_max_f32_e32 v221, 0, v221
	v_max_f32_e32 v222, 0, v222
	v_max_f32_e32 v223, 0, v223
	v_max_f32_e32 v224, 0, v224
	v_max_f32_e32 v225, 0, v225
	v_max_f32_e32 v226, 0, v226
	v_max_f32_e32 v227, 0, v227
	v_max_f32_e32 v228, 0, v228
	v_max_f32_e32 v229, 0, v229
	v_max_f32_e32 v230, 0, v230
	v_max_f32_e32 v231, 0, v231
	v_max_f32_e32 v232, 0, v232
	v_max_f32_e32 v233, 0, v233
	v_max_f32_e32 v234, 0, v234
	v_max_f32_e32 v235, 0, v235
	v_sqrt_f32_e32 v220, v220
	v_sqrt_f32_e32 v221, v221
	v_sqrt_f32_e32 v222, v222
	v_sqrt_f32_e32 v223, v223
	v_sqrt_f32_e32 v224, v224
	v_sqrt_f32_e32 v225, v225
	v_sqrt_f32_e32 v226, v226
	v_sqrt_f32_e32 v227, v227
	v_sqrt_f32_e32 v228, v228
	v_sqrt_f32_e32 v229, v229
	v_sqrt_f32_e32 v230, v230
	v_sqrt_f32_e32 v231, v231
	v_sqrt_f32_e32 v232, v232
	v_sqrt_f32_e32 v233, v233
	v_sqrt_f32_e32 v234, v234
	v_sqrt_f32_e32 v235, v235
	v_pk_mul_f32 v[84:85], v[84:85], v[220:221]
	v_pk_mul_f32 v[86:87], v[86:87], v[222:223]
	v_pk_mul_f32 v[76:77], v[76:77], v[224:225]
	v_pk_mul_f32 v[78:79], v[78:79], v[226:227]
	v_pk_mul_f32 v[52:53], v[52:53], v[228:229]
	v_pk_mul_f32 v[54:55], v[54:55], v[230:231]
	v_pk_mul_f32 v[32:33], v[32:33], v[232:233]
	v_pk_mul_f32 v[34:35], v[34:35], v[234:235]
	v_lshlrev_b32_e32 v220, 16, v132
	v_and_b32_e32 v221, 0xffff0000, v132
	v_lshlrev_b32_e32 v222, 16, v133
	v_and_b32_e32 v223, 0xffff0000, v133
	v_lshlrev_b32_e32 v224, 16, v134
	v_and_b32_e32 v225, 0xffff0000, v134
	v_lshlrev_b32_e32 v226, 16, v135
	v_and_b32_e32 v227, 0xffff0000, v135
	v_lshlrev_b32_e32 v228, 16, v112
	v_and_b32_e32 v229, 0xffff0000, v112
	v_lshlrev_b32_e32 v230, 16, v113
	v_and_b32_e32 v231, 0xffff0000, v113
	v_lshlrev_b32_e32 v232, 16, v114
	v_and_b32_e32 v233, 0xffff0000, v114
	v_lshlrev_b32_e32 v234, 16, v115
	v_and_b32_e32 v235, 0xffff0000, v115
	v_pk_mul_f32 v[84:85], v[84:85], v[220:221]
	v_pk_mul_f32 v[86:87], v[86:87], v[222:223]
	v_pk_mul_f32 v[76:77], v[76:77], v[224:225]
	v_pk_mul_f32 v[78:79], v[78:79], v[226:227]
	v_pk_mul_f32 v[52:53], v[52:53], v[228:229]
	v_pk_mul_f32 v[54:55], v[54:55], v[230:231]
	v_pk_mul_f32 v[32:33], v[32:33], v[232:233]
	v_pk_mul_f32 v[34:35], v[34:35], v[234:235]
	v_cvt_pk_bf16_f32 v220, v88, v89
	v_cvt_pk_bf16_f32 v221, v90, v91
	v_cvt_pk_bf16_f32 v222, v80, v81
	v_cvt_pk_bf16_f32 v223, v82, v83
	v_cvt_pk_bf16_f32 v228, v56, v57
	v_cvt_pk_bf16_f32 v229, v58, v59
	v_cvt_pk_bf16_f32 v230, v36, v37
	v_cvt_pk_bf16_f32 v231, v38, v39
	v_cvt_pk_bf16_f32 v224, v84, v85
	v_cvt_pk_bf16_f32 v225, v86, v87
	v_cvt_pk_bf16_f32 v226, v76, v77
	v_cvt_pk_bf16_f32 v227, v78, v79
	v_cvt_pk_bf16_f32 v232, v52, v53
	v_cvt_pk_bf16_f32 v233, v54, v55
	v_cvt_pk_bf16_f32 v234, v32, v33
	v_cvt_pk_bf16_f32 v235, v34, v35
	s_add_i32 s0, s44, 32
	s_ashr_i32 s1, s0, 31
	s_lshl_b64 s[0:1], s[0:1], 14
	v_mov_b32_e32 v205, s1
	v_or_b32_e32 v204, s0, v190
	v_lshl_add_u64 v[206:207], v[204:205], 0, v[192:193]
	v_lshlrev_b64 v[206:207], 1, v[206:207]
	v_lshl_add_u64 v[208:209], s[18:19], 0, v[206:207]
	v_lshl_add_u64 v[236:237], s[20:21], 0, v[206:207]
	global_store_dwordx4 v[208:209], v[220:223], off
	global_store_dwordx4 v[236:237], v[224:227], off
	v_lshl_add_u64 v[206:207], v[204:205], 0, v[194:195]
	v_lshlrev_b64 v[206:207], 1, v[206:207]
	v_lshl_add_u64 v[208:209], s[18:19], 0, v[206:207]
	v_lshl_add_u64 v[236:237], s[20:21], 0, v[206:207]
	global_store_dwordx4 v[208:209], v[228:231], off
	global_store_dwordx4 v[236:237], v[232:235], off
	v_pk_add_f32 v[28:29], v[28:29], v[64:65]
	v_pk_add_f32 v[24:25], v[24:25], v[68:69]
	v_pk_add_f32 v[30:31], v[30:31], v[66:67]
	v_pk_add_f32 v[26:27], v[26:27], v[70:71]
	v_pk_add_f32 v[20:21], v[20:21], v[48:49]
	v_pk_add_f32 v[16:17], v[16:17], v[44:45]
	v_pk_add_f32 v[22:23], v[22:23], v[50:51]
	v_pk_add_f32 v[18:19], v[18:19], v[46:47]
	v_pk_add_f32 v[12:13], v[12:13], v[64:65]
	v_pk_add_f32 v[8:9], v[8:9], v[68:69]
	v_pk_add_f32 v[14:15], v[14:15], v[66:67]
	v_pk_add_f32 v[10:11], v[10:11], v[70:71]
	v_pk_add_f32 v[4:5], v[4:5], v[48:49]
	v_pk_add_f32 v[0:1], v[0:1], v[44:45]
	v_pk_add_f32 v[6:7], v[6:7], v[50:51]
	v_pk_add_f32 v[2:3], v[2:3], v[46:47]
	v_pk_mul_f32 v[28:29], v[28:29], s[24:25] op_sel_hi:[1,0]
	v_pk_mul_f32 v[24:25], v[24:25], s[24:25] op_sel_hi:[1,0]
	v_pk_mul_f32 v[30:31], v[30:31], s[24:25] op_sel_hi:[1,0]
	v_pk_mul_f32 v[26:27], v[26:27], s[24:25] op_sel_hi:[1,0]
	v_pk_mul_f32 v[20:21], v[20:21], s[24:25] op_sel_hi:[1,0]
	v_pk_mul_f32 v[16:17], v[16:17], s[24:25] op_sel_hi:[1,0]
	v_pk_mul_f32 v[22:23], v[22:23], s[24:25] op_sel_hi:[1,0]
	v_pk_mul_f32 v[18:19], v[18:19], s[24:25] op_sel_hi:[1,0]
	v_pk_mul_f32 v[12:13], v[12:13], s[24:25] op_sel_hi:[1,0]
	v_pk_mul_f32 v[8:9], v[8:9], s[24:25] op_sel_hi:[1,0]
	v_pk_mul_f32 v[14:15], v[14:15], s[24:25] op_sel_hi:[1,0]
	v_pk_mul_f32 v[10:11], v[10:11], s[24:25] op_sel_hi:[1,0]
	v_pk_mul_f32 v[4:5], v[4:5], s[24:25] op_sel_hi:[1,0]
	v_pk_mul_f32 v[0:1], v[0:1], s[24:25] op_sel_hi:[1,0]
	v_pk_mul_f32 v[6:7], v[6:7], s[24:25] op_sel_hi:[1,0]
	v_pk_mul_f32 v[2:3], v[2:3], s[24:25] op_sel_hi:[1,0]
	v_exp_f32_e32 v28, v28
	v_exp_f32_e32 v29, v29
	v_exp_f32_e32 v24, v24
	v_exp_f32_e32 v25, v25
	v_exp_f32_e32 v30, v30
	v_exp_f32_e32 v31, v31
	v_exp_f32_e32 v26, v26
	v_exp_f32_e32 v27, v27
	v_exp_f32_e32 v20, v20
	v_exp_f32_e32 v21, v21
	v_exp_f32_e32 v16, v16
	v_exp_f32_e32 v17, v17
	v_exp_f32_e32 v22, v22
	v_exp_f32_e32 v23, v23
	v_exp_f32_e32 v18, v18
	v_exp_f32_e32 v19, v19
	v_exp_f32_e32 v12, v12
	v_exp_f32_e32 v13, v13
	v_exp_f32_e32 v8, v8
	v_exp_f32_e32 v9, v9
	v_exp_f32_e32 v14, v14
	v_exp_f32_e32 v15, v15
	v_exp_f32_e32 v10, v10
	v_exp_f32_e32 v11, v11
	v_exp_f32_e32 v4, v4
	v_exp_f32_e32 v5, v5
	v_exp_f32_e32 v0, v0
	v_exp_f32_e32 v1, v1
	v_exp_f32_e32 v6, v6
	v_exp_f32_e32 v7, v7
	v_exp_f32_e32 v2, v2
	v_exp_f32_e32 v3, v3
	v_pk_add_f32 v[28:29], v[28:29], 1.0 op_sel_hi:[1,0]
	v_pk_add_f32 v[24:25], v[24:25], 1.0 op_sel_hi:[1,0]
	v_pk_add_f32 v[30:31], v[30:31], 1.0 op_sel_hi:[1,0]
	v_pk_add_f32 v[26:27], v[26:27], 1.0 op_sel_hi:[1,0]
	v_pk_add_f32 v[20:21], v[20:21], 1.0 op_sel_hi:[1,0]
	v_pk_add_f32 v[16:17], v[16:17], 1.0 op_sel_hi:[1,0]
	v_pk_add_f32 v[22:23], v[22:23], 1.0 op_sel_hi:[1,0]
	v_pk_add_f32 v[18:19], v[18:19], 1.0 op_sel_hi:[1,0]
	v_pk_add_f32 v[12:13], v[12:13], 1.0 op_sel_hi:[1,0]
	v_pk_add_f32 v[8:9], v[8:9], 1.0 op_sel_hi:[1,0]
	v_pk_add_f32 v[14:15], v[14:15], 1.0 op_sel_hi:[1,0]
	v_pk_add_f32 v[10:11], v[10:11], 1.0 op_sel_hi:[1,0]
	v_pk_add_f32 v[4:5], v[4:5], 1.0 op_sel_hi:[1,0]
	v_pk_add_f32 v[0:1], v[0:1], 1.0 op_sel_hi:[1,0]
	v_pk_add_f32 v[6:7], v[6:7], 1.0 op_sel_hi:[1,0]
	v_pk_add_f32 v[2:3], v[2:3], 1.0 op_sel_hi:[1,0]
	v_rcp_f32_e32 v28, v28
	v_rcp_f32_e32 v29, v29
	v_rcp_f32_e32 v24, v24
	v_rcp_f32_e32 v25, v25
	v_rcp_f32_e32 v30, v30
	v_rcp_f32_e32 v31, v31
	v_rcp_f32_e32 v26, v26
	v_rcp_f32_e32 v27, v27
	v_rcp_f32_e32 v20, v20
	v_rcp_f32_e32 v21, v21
	v_rcp_f32_e32 v16, v16
	v_rcp_f32_e32 v17, v17
	v_rcp_f32_e32 v22, v22
	v_rcp_f32_e32 v23, v23
	v_rcp_f32_e32 v18, v18
	v_rcp_f32_e32 v19, v19
	v_rcp_f32_e32 v12, v12
	v_rcp_f32_e32 v13, v13
	v_rcp_f32_e32 v8, v8
	v_rcp_f32_e32 v9, v9
	v_rcp_f32_e32 v14, v14
	v_rcp_f32_e32 v15, v15
	v_rcp_f32_e32 v10, v10
	v_rcp_f32_e32 v11, v11
	v_rcp_f32_e32 v4, v4
	v_rcp_f32_e32 v5, v5
	v_rcp_f32_e32 v0, v0
	v_rcp_f32_e32 v1, v1
	v_rcp_f32_e32 v6, v6
	v_rcp_f32_e32 v7, v7
	v_rcp_f32_e32 v2, v2
	v_rcp_f32_e32 v3, v3
	v_pk_mul_f32 v[28:29], v[60:61], v[28:29] neg_lo:[1,0] neg_hi:[1,0]
	v_pk_mul_f32 v[30:31], v[62:63], v[30:31] neg_lo:[1,0] neg_hi:[1,0]
	v_pk_mul_f32 v[20:21], v[40:41], v[20:21] neg_lo:[1,0] neg_hi:[1,0]
	v_pk_mul_f32 v[22:23], v[42:43], v[22:23] neg_lo:[1,0] neg_hi:[1,0]
	v_pk_mul_f32 v[12:13], v[60:61], v[12:13] neg_lo:[1,0] neg_hi:[1,0]
	v_pk_mul_f32 v[14:15], v[62:63], v[14:15] neg_lo:[1,0] neg_hi:[1,0]
	v_pk_mul_f32 v[4:5], v[40:41], v[4:5] neg_lo:[1,0] neg_hi:[1,0]
	v_pk_mul_f32 v[6:7], v[42:43], v[6:7] neg_lo:[1,0] neg_hi:[1,0]
	v_pk_mul_f32 v[220:221], v[28:29], s[26:27] op_sel_hi:[1,0]
	v_pk_mul_f32 v[222:223], v[30:31], s[26:27] op_sel_hi:[1,0]
	v_pk_mul_f32 v[224:225], v[20:21], s[26:27] op_sel_hi:[1,0]
	v_pk_mul_f32 v[226:227], v[22:23], s[26:27] op_sel_hi:[1,0]
	v_pk_mul_f32 v[228:229], v[12:13], s[26:27] op_sel_hi:[1,0]
	v_pk_mul_f32 v[230:231], v[14:15], s[26:27] op_sel_hi:[1,0]
	v_pk_mul_f32 v[232:233], v[4:5], s[26:27] op_sel_hi:[1,0]
	v_pk_mul_f32 v[234:235], v[6:7], s[26:27] op_sel_hi:[1,0]
	v_exp_f32_e32 v220, v220
	v_exp_f32_e32 v221, v221
	v_exp_f32_e32 v222, v222
	v_exp_f32_e32 v223, v223
	v_exp_f32_e32 v224, v224
	v_exp_f32_e32 v225, v225
	v_exp_f32_e32 v226, v226
	v_exp_f32_e32 v227, v227
	v_exp_f32_e32 v228, v228
	v_exp_f32_e32 v229, v229
	v_exp_f32_e32 v230, v230
	v_exp_f32_e32 v231, v231
	v_exp_f32_e32 v232, v232
	v_exp_f32_e32 v233, v233
	v_exp_f32_e32 v234, v234
	v_exp_f32_e32 v235, v235
	v_pk_add_f32 v[220:221], v[220:221], 1.0 op_sel_hi:[1,0] neg_lo:[1,0] neg_hi:[1,0]
	v_pk_add_f32 v[222:223], v[222:223], 1.0 op_sel_hi:[1,0] neg_lo:[1,0] neg_hi:[1,0]
	v_pk_add_f32 v[224:225], v[224:225], 1.0 op_sel_hi:[1,0] neg_lo:[1,0] neg_hi:[1,0]
	v_pk_add_f32 v[226:227], v[226:227], 1.0 op_sel_hi:[1,0] neg_lo:[1,0] neg_hi:[1,0]
	v_pk_add_f32 v[228:229], v[228:229], 1.0 op_sel_hi:[1,0] neg_lo:[1,0] neg_hi:[1,0]
	v_pk_add_f32 v[230:231], v[230:231], 1.0 op_sel_hi:[1,0] neg_lo:[1,0] neg_hi:[1,0]
	v_pk_add_f32 v[232:233], v[232:233], 1.0 op_sel_hi:[1,0] neg_lo:[1,0] neg_hi:[1,0]
	v_pk_add_f32 v[234:235], v[234:235], 1.0 op_sel_hi:[1,0] neg_lo:[1,0] neg_hi:[1,0]
	v_max_f32_e32 v220, 0, v220
	v_max_f32_e32 v221, 0, v221
	v_max_f32_e32 v222, 0, v222
	v_max_f32_e32 v223, 0, v223
	v_max_f32_e32 v224, 0, v224
	v_max_f32_e32 v225, 0, v225
	v_max_f32_e32 v226, 0, v226
	v_max_f32_e32 v227, 0, v227
	v_max_f32_e32 v228, 0, v228
	v_max_f32_e32 v229, 0, v229
	v_max_f32_e32 v230, 0, v230
	v_max_f32_e32 v231, 0, v231
	v_max_f32_e32 v232, 0, v232
	v_max_f32_e32 v233, 0, v233
	v_max_f32_e32 v234, 0, v234
	v_max_f32_e32 v235, 0, v235
	v_sqrt_f32_e32 v220, v220
	v_sqrt_f32_e32 v221, v221
	v_sqrt_f32_e32 v222, v222
	v_sqrt_f32_e32 v223, v223
	v_sqrt_f32_e32 v224, v224
	v_sqrt_f32_e32 v225, v225
	v_sqrt_f32_e32 v226, v226
	v_sqrt_f32_e32 v227, v227
	v_sqrt_f32_e32 v228, v228
	v_sqrt_f32_e32 v229, v229
	v_sqrt_f32_e32 v230, v230
	v_sqrt_f32_e32 v231, v231
	v_sqrt_f32_e32 v232, v232
	v_sqrt_f32_e32 v233, v233
	v_sqrt_f32_e32 v234, v234
	v_sqrt_f32_e32 v235, v235
	v_pk_mul_f32 v[24:25], v[24:25], v[220:221]
	v_pk_mul_f32 v[26:27], v[26:27], v[222:223]
	v_pk_mul_f32 v[16:17], v[16:17], v[224:225]
	v_pk_mul_f32 v[18:19], v[18:19], v[226:227]
	v_pk_mul_f32 v[8:9], v[8:9], v[228:229]
	v_pk_mul_f32 v[10:11], v[10:11], v[230:231]
	v_pk_mul_f32 v[0:1], v[0:1], v[232:233]
	v_pk_mul_f32 v[2:3], v[2:3], v[234:235]
	v_lshlrev_b32_e32 v220, 16, v92
	v_and_b32_e32 v221, 0xffff0000, v92
	v_lshlrev_b32_e32 v222, 16, v93
	v_and_b32_e32 v223, 0xffff0000, v93
	v_lshlrev_b32_e32 v224, 16, v94
	v_and_b32_e32 v225, 0xffff0000, v94
	v_lshlrev_b32_e32 v226, 16, v95
	v_and_b32_e32 v227, 0xffff0000, v95
	v_lshlrev_b32_e32 v228, 16, v72
	v_and_b32_e32 v229, 0xffff0000, v72
	v_lshlrev_b32_e32 v230, 16, v73
	v_and_b32_e32 v231, 0xffff0000, v73
	v_lshlrev_b32_e32 v232, 16, v74
	v_and_b32_e32 v233, 0xffff0000, v74
	v_lshlrev_b32_e32 v234, 16, v75
	v_and_b32_e32 v235, 0xffff0000, v75
	v_pk_mul_f32 v[24:25], v[24:25], v[220:221]
	v_pk_mul_f32 v[26:27], v[26:27], v[222:223]
	v_pk_mul_f32 v[16:17], v[16:17], v[224:225]
	v_pk_mul_f32 v[18:19], v[18:19], v[226:227]
	v_pk_mul_f32 v[8:9], v[8:9], v[228:229]
	v_pk_mul_f32 v[10:11], v[10:11], v[230:231]
	v_pk_mul_f32 v[0:1], v[0:1], v[232:233]
	v_pk_mul_f32 v[2:3], v[2:3], v[234:235]
	v_cvt_pk_bf16_f32 v220, v28, v29
	v_cvt_pk_bf16_f32 v221, v30, v31
	v_cvt_pk_bf16_f32 v222, v20, v21
	v_cvt_pk_bf16_f32 v223, v22, v23
	v_cvt_pk_bf16_f32 v228, v12, v13
	v_cvt_pk_bf16_f32 v229, v14, v15
	v_cvt_pk_bf16_f32 v230, v4, v5
	v_cvt_pk_bf16_f32 v231, v6, v7
	v_cvt_pk_bf16_f32 v224, v24, v25
	v_cvt_pk_bf16_f32 v225, v26, v27
	v_cvt_pk_bf16_f32 v226, v16, v17
	v_cvt_pk_bf16_f32 v227, v18, v19
	v_cvt_pk_bf16_f32 v232, v8, v9
	v_cvt_pk_bf16_f32 v233, v10, v11
	v_cvt_pk_bf16_f32 v234, v0, v1
	v_cvt_pk_bf16_f32 v235, v2, v3
	v_lshl_add_u64 v[206:207], v[204:205], 0, v[196:197]
	v_lshlrev_b64 v[206:207], 1, v[206:207]
	v_lshl_add_u64 v[208:209], s[18:19], 0, v[206:207]
	v_lshl_add_u64 v[236:237], s[20:21], 0, v[206:207]
	global_store_dwordx4 v[208:209], v[220:223], off
	global_store_dwordx4 v[236:237], v[224:227], off
	v_lshl_add_u64 v[206:207], v[204:205], 0, v[198:199]
	v_lshlrev_b64 v[206:207], 1, v[206:207]
	v_lshl_add_u64 v[208:209], s[18:19], 0, v[206:207]
	v_lshl_add_u64 v[236:237], s[20:21], 0, v[206:207]
	global_store_dwordx4 v[208:209], v[228:231], off
	global_store_dwordx4 v[236:237], v[232:235], off
	s_mov_b64 s[8:9], s[38:39]
	s_mov_b64 s[44:45], s[34:35]
	s_mov_b32 s1, s28
	s_mov_b32 s0, s30
	s_and_b64 vcc, exec, s[6:7]
	s_cbranch_vccz .LBB0_459
	s_waitcnt vmcnt(0)
	s_cmpk_gt_u32 s10, 0xff
	s_cbranch_scc1 .LBB0_470
	s_barrier

.LBB0_480:
	s_lshl_b32 s6, s9, 6
	s_and_b32 s4, s16, 32
	s_add_i32 s5, s8, s6
	s_add_i32 s18, s5, s4
	s_ashr_i32 s19, s18, 31
	s_lshl_b64 s[18:19], s[18:19], 15
	v_mov_b32_e32 v10, 0
	v_mov_b32_e32 v11, v10
	v_mov_b32_e32 v8, v10
	v_mov_b32_e32 v9, v10
	v_lshl_add_u64 v[16:17], v[0:1], 0, s[18:19]
	v_add_co_u32_e32 v16, vcc, 0x100, v16
	s_nop 1
	v_addc_co_u32_e32 v17, vcc, 0, v17, vcc
	v_add_co_u32_e32 v18, vcc, 0xfc000000, v16
	s_nop 1
	v_addc_co_u32_e32 v19, vcc, -1, v17, vcc
	global_load_dword v44, v[18:19], off offset:-4096
	global_load_dword v45, v[16:17], off offset:-4096
	global_load_dword v46, v[18:19], off offset:-3840
	global_load_dword v47, v[16:17], off offset:-3840
	global_load_dword v48, v[18:19], off offset:-3584
	global_load_dword v49, v[16:17], off offset:-3584
	global_load_dword v50, v[18:19], off offset:-3328
	global_load_dword v51, v[16:17], off offset:-3328
	global_load_dword v52, v[18:19], off offset:-3072
	global_load_dword v53, v[16:17], off offset:-3072
	global_load_dword v54, v[18:19], off offset:-2816
	global_load_dword v55, v[16:17], off offset:-2816
	global_load_dword v56, v[18:19], off offset:-2560
	global_load_dword v57, v[16:17], off offset:-2560
	global_load_dword v58, v[18:19], off offset:-2304
	global_load_dword v59, v[16:17], off offset:-2304
	global_load_dword v60, v[18:19], off offset:-2048
	global_load_dword v61, v[16:17], off offset:-2048
	global_load_dword v62, v[18:19], off offset:-1792
	global_load_dword v63, v[16:17], off offset:-1792
	global_load_dword v64, v[18:19], off offset:-1536
	global_load_dword v65, v[16:17], off offset:-1536
	global_load_dword v66, v[18:19], off offset:-1280
	global_load_dword v67, v[16:17], off offset:-1280
	global_load_dword v68, v[18:19], off offset:-1024
	global_load_dword v69, v[16:17], off offset:-1024
	global_load_dword v70, v[18:19], off offset:-768
	global_load_dword v71, v[16:17], off offset:-768
	global_load_dword v72, v[18:19], off offset:-512
	global_load_dword v73, v[16:17], off offset:-512
	global_load_dword v74, v[18:19], off offset:-256
	global_load_dword v75, v[16:17], off offset:-256
	global_load_dword v76, v[18:19], off
	global_load_dword v77, v[16:17], off
	global_load_dword v78, v[18:19], off offset:256
	global_load_dword v79, v[16:17], off offset:256
	global_load_dword v80, v[18:19], off offset:512
	global_load_dword v81, v[16:17], off offset:512
	global_load_dword v82, v[18:19], off offset:768
	global_load_dword v83, v[16:17], off offset:768
	global_load_dword v84, v[18:19], off offset:1024
	global_load_dword v85, v[16:17], off offset:1024
	global_load_dword v86, v[18:19], off offset:1280
	global_load_dword v87, v[16:17], off offset:1280
	global_load_dword v88, v[18:19], off offset:1536
	global_load_dword v89, v[16:17], off offset:1536
	global_load_dword v90, v[18:19], off offset:1792
	global_load_dword v91, v[16:17], off offset:1792
	s_waitcnt vmcnt(46)
	v_lshlrev_b32_e32 v20, 16, v44
	v_and_b32_e32 v21, 0xffff0000, v44
	v_lshlrev_b32_e32 v22, 16, v45
	v_and_b32_e32 v23, 0xffff0000, v45
	v_mul_f32_e32 v24, 0x3fb8aa3b, v20
	v_mul_f32_e32 v25, 0x3fb8aa3b, v21
	global_load_dword v92, v[18:19], off offset:2048
	global_load_dword v93, v[16:17], off offset:2048
	v_exp_f32_e32 v24, v24
	v_exp_f32_e32 v25, v25
	s_waitcnt vmcnt(46)
	v_lshlrev_b32_e32 v26, 16, v46
	v_and_b32_e32 v27, 0xffff0000, v46
	v_lshlrev_b32_e32 v28, 16, v47
	v_and_b32_e32 v29, 0xffff0000, v47
	v_mul_f32_e32 v30, 0x3fb8aa3b, v26
	v_mul_f32_e32 v31, 0x3fb8aa3b, v27
	v_pk_add_f32 v[10:11], v[10:11], v[20:21]
	v_pk_fma_f32 v[8:9], v[8:9], v[24:25], v[22:23]
	global_load_dword v94, v[18:19], off offset:2304
	global_load_dword v95, v[16:17], off offset:2304
	v_exp_f32_e32 v30, v30
	v_exp_f32_e32 v31, v31
	s_waitcnt vmcnt(46)
	v_lshlrev_b32_e32 v32, 16, v48
	v_and_b32_e32 v33, 0xffff0000, v48
	v_lshlrev_b32_e32 v34, 16, v49
	v_and_b32_e32 v35, 0xffff0000, v49
	v_mul_f32_e32 v36, 0x3fb8aa3b, v32
	v_mul_f32_e32 v37, 0x3fb8aa3b, v33
	v_pk_add_f32 v[10:11], v[10:11], v[26:27]
	v_pk_fma_f32 v[8:9], v[8:9], v[30:31], v[28:29]
	global_load_dword v96, v[18:19], off offset:2560
	global_load_dword v97, v[16:17], off offset:2560
	v_exp_f32_e32 v36, v36
	v_exp_f32_e32 v37, v37
	s_waitcnt vmcnt(46)
	v_lshlrev_b32_e32 v38, 16, v50
	v_and_b32_e32 v39, 0xffff0000, v50
	v_lshlrev_b32_e32 v40, 16, v51
	v_and_b32_e32 v41, 0xffff0000, v51
	v_mul_f32_e32 v42, 0x3fb8aa3b, v38
	v_mul_f32_e32 v43, 0x3fb8aa3b, v39
	v_pk_add_f32 v[10:11], v[10:11], v[32:33]
	v_pk_fma_f32 v[8:9], v[8:9], v[36:37], v[34:35]
	global_load_dword v98, v[18:19], off offset:2816
	global_load_dword v99, v[16:17], off offset:2816
	v_exp_f32_e32 v42, v42
	v_exp_f32_e32 v43, v43
	s_waitcnt vmcnt(46)
	v_lshlrev_b32_e32 v20, 16, v52
	v_and_b32_e32 v21, 0xffff0000, v52
	v_lshlrev_b32_e32 v22, 16, v53
	v_and_b32_e32 v23, 0xffff0000, v53
	v_mul_f32_e32 v24, 0x3fb8aa3b, v20
	v_mul_f32_e32 v25, 0x3fb8aa3b, v21
	v_pk_add_f32 v[10:11], v[10:11], v[38:39]
	v_pk_fma_f32 v[8:9], v[8:9], v[42:43], v[40:41]
	global_load_dword v100, v[18:19], off offset:3072
	global_load_dword v101, v[16:17], off offset:3072
	v_exp_f32_e32 v24, v24
	v_exp_f32_e32 v25, v25
	s_waitcnt vmcnt(46)
	v_lshlrev_b32_e32 v26, 16, v54
	v_and_b32_e32 v27, 0xffff0000, v54
	v_lshlrev_b32_e32 v28, 16, v55
	v_and_b32_e32 v29, 0xffff0000, v55
	v_mul_f32_e32 v30, 0x3fb8aa3b, v26
	v_mul_f32_e32 v31, 0x3fb8aa3b, v27
	v_pk_add_f32 v[10:11], v[10:11], v[20:21]
	v_pk_fma_f32 v[8:9], v[8:9], v[24:25], v[22:23]
	global_load_dword v102, v[18:19], off offset:3328
	global_load_dword v103, v[16:17], off offset:3328
	v_exp_f32_e32 v30, v30
	v_exp_f32_e32 v31, v31
	s_waitcnt vmcnt(46)
	v_lshlrev_b32_e32 v32, 16, v56
	v_and_b32_e32 v33, 0xffff0000, v56
	v_lshlrev_b32_e32 v34, 16, v57
	v_and_b32_e32 v35, 0xffff0000, v57
	v_mul_f32_e32 v36, 0x3fb8aa3b, v32
	v_mul_f32_e32 v37, 0x3fb8aa3b, v33
	v_pk_add_f32 v[10:11], v[10:11], v[26:27]
	v_pk_fma_f32 v[8:9], v[8:9], v[30:31], v[28:29]
	global_load_dword v104, v[18:19], off offset:3584
	global_load_dword v105, v[16:17], off offset:3584
	v_exp_f32_e32 v36, v36
	v_exp_f32_e32 v37, v37
	s_waitcnt vmcnt(46)
	v_lshlrev_b32_e32 v38, 16, v58
	v_and_b32_e32 v39, 0xffff0000, v58
	v_lshlrev_b32_e32 v40, 16, v59
	v_and_b32_e32 v41, 0xffff0000, v59
	v_mul_f32_e32 v42, 0x3fb8aa3b, v38
	v_mul_f32_e32 v43, 0x3fb8aa3b, v39
	v_pk_add_f32 v[10:11], v[10:11], v[32:33]
	v_pk_fma_f32 v[8:9], v[8:9], v[36:37], v[34:35]
	global_load_dword v106, v[18:19], off offset:3840
	global_load_dword v107, v[16:17], off offset:3840
	v_exp_f32_e32 v42, v42
	v_exp_f32_e32 v43, v43
	s_waitcnt vmcnt(46)
	v_lshlrev_b32_e32 v20, 16, v60
	v_and_b32_e32 v21, 0xffff0000, v60
	v_lshlrev_b32_e32 v22, 16, v61
	v_and_b32_e32 v23, 0xffff0000, v61
	v_mul_f32_e32 v24, 0x3fb8aa3b, v20
	v_mul_f32_e32 v25, 0x3fb8aa3b, v21
	v_pk_add_f32 v[10:11], v[10:11], v[38:39]
	v_pk_fma_f32 v[8:9], v[8:9], v[42:43], v[40:41]
	v_lshl_add_u64 v[18:19], v[18:19], 0, s[0:1]
	v_lshl_add_u64 v[18:19], v[18:19], 0, s[0:1]
	v_lshl_add_u64 v[16:17], v[16:17], 0, s[0:1]
	v_lshl_add_u64 v[16:17], v[16:17], 0, s[0:1]
	global_load_dword v44, v[18:19], off offset:-4096
	global_load_dword v45, v[16:17], off offset:-4096
	v_exp_f32_e32 v24, v24
	v_exp_f32_e32 v25, v25
	s_waitcnt vmcnt(46)
	v_lshlrev_b32_e32 v26, 16, v62
	v_and_b32_e32 v27, 0xffff0000, v62
	v_lshlrev_b32_e32 v28, 16, v63
	v_and_b32_e32 v29, 0xffff0000, v63
	v_mul_f32_e32 v30, 0x3fb8aa3b, v26
	v_mul_f32_e32 v31, 0x3fb8aa3b, v27
	v_pk_add_f32 v[10:11], v[10:11], v[20:21]
	v_pk_fma_f32 v[8:9], v[8:9], v[24:25], v[22:23]
	global_load_dword v46, v[18:19], off offset:-3840
	global_load_dword v47, v[16:17], off offset:-3840
	v_exp_f32_e32 v30, v30
	v_exp_f32_e32 v31, v31
	s_waitcnt vmcnt(46)
	v_lshlrev_b32_e32 v32, 16, v64
	v_and_b32_e32 v33, 0xffff0000, v64
	v_lshlrev_b32_e32 v34, 16, v65
	v_and_b32_e32 v35, 0xffff0000, v65
	v_mul_f32_e32 v36, 0x3fb8aa3b, v32
	v_mul_f32_e32 v37, 0x3fb8aa3b, v33
	v_pk_add_f32 v[10:11], v[10:11], v[26:27]
	v_pk_fma_f32 v[8:9], v[8:9], v[30:31], v[28:29]
	global_load_dword v48, v[18:19], off offset:-3584
	global_load_dword v49, v[16:17], off offset:-3584
	v_exp_f32_e32 v36, v36
	v_exp_f32_e32 v37, v37
	s_waitcnt vmcnt(46)
	v_lshlrev_b32_e32 v38, 16, v66
	v_and_b32_e32 v39, 0xffff0000, v66
	v_lshlrev_b32_e32 v40, 16, v67
	v_and_b32_e32 v41, 0xffff0000, v67
	v_mul_f32_e32 v42, 0x3fb8aa3b, v38
	v_mul_f32_e32 v43, 0x3fb8aa3b, v39
	v_pk_add_f32 v[10:11], v[10:11], v[32:33]
	v_pk_fma_f32 v[8:9], v[8:9], v[36:37], v[34:35]
	global_load_dword v50, v[18:19], off offset:-3328
	global_load_dword v51, v[16:17], off offset:-3328
	v_exp_f32_e32 v42, v42
	v_exp_f32_e32 v43, v43
	s_waitcnt vmcnt(46)
	v_lshlrev_b32_e32 v20, 16, v68
	v_and_b32_e32 v21, 0xffff0000, v68
	v_lshlrev_b32_e32 v22, 16, v69
	v_and_b32_e32 v23, 0xffff0000, v69
	v_mul_f32_e32 v24, 0x3fb8aa3b, v20
	v_mul_f32_e32 v25, 0x3fb8aa3b, v21
	v_pk_add_f32 v[10:11], v[10:11], v[38:39]
	v_pk_fma_f32 v[8:9], v[8:9], v[42:43], v[40:41]
	global_load_dword v52, v[18:19], off offset:-3072
	global_load_dword v53, v[16:17], off offset:-3072
	v_exp_f32_e32 v24, v24
	v_exp_f32_e32 v25, v25
	s_waitcnt vmcnt(46)
	v_lshlrev_b32_e32 v26, 16, v70
	v_and_b32_e32 v27, 0xffff0000, v70
	v_lshlrev_b32_e32 v28, 16, v71
	v_and_b32_e32 v29, 0xffff0000, v71
	v_mul_f32_e32 v30, 0x3fb8aa3b, v26
	v_mul_f32_e32 v31, 0x3fb8aa3b, v27
	v_pk_add_f32 v[10:11], v[10:11], v[20:21]
	v_pk_fma_f32 v[8:9], v[8:9], v[24:25], v[22:23]
	global_load_dword v54, v[18:19], off offset:-2816
	global_load_dword v55, v[16:17], off offset:-2816
	v_exp_f32_e32 v30, v30
	v_exp_f32_e32 v31, v31
	s_waitcnt vmcnt(46)
	v_lshlrev_b32_e32 v32, 16, v72
	v_and_b32_e32 v33, 0xffff0000, v72
	v_lshlrev_b32_e32 v34, 16, v73
	v_and_b32_e32 v35, 0xffff0000, v73
	v_mul_f32_e32 v36, 0x3fb8aa3b, v32
	v_mul_f32_e32 v37, 0x3fb8aa3b, v33
	v_pk_add_f32 v[10:11], v[10:11], v[26:27]
	v_pk_fma_f32 v[8:9], v[8:9], v[30:31], v[28:29]
	global_load_dword v56, v[18:19], off offset:-2560
	global_load_dword v57, v[16:17], off offset:-2560
	v_exp_f32_e32 v36, v36
	v_exp_f32_e32 v37, v37
	s_waitcnt vmcnt(46)
	v_lshlrev_b32_e32 v38, 16, v74
	v_and_b32_e32 v39, 0xffff0000, v74
	v_lshlrev_b32_e32 v40, 16, v75
	v_and_b32_e32 v41, 0xffff0000, v75
	v_mul_f32_e32 v42, 0x3fb8aa3b, v38
	v_mul_f32_e32 v43, 0x3fb8aa3b, v39
	v_pk_add_f32 v[10:11], v[10:11], v[32:33]
	v_pk_fma_f32 v[8:9], v[8:9], v[36:37], v[34:35]
	global_load_dword v58, v[18:19], off offset:-2304
	global_load_dword v59, v[16:17], off offset:-2304
	v_exp_f32_e32 v42, v42
	v_exp_f32_e32 v43, v43
	s_waitcnt vmcnt(46)
	v_lshlrev_b32_e32 v20, 16, v76
	v_and_b32_e32 v21, 0xffff0000, v76
	v_lshlrev_b32_e32 v22, 16, v77
	v_and_b32_e32 v23, 0xffff0000, v77
	v_mul_f32_e32 v24, 0x3fb8aa3b, v20
	v_mul_f32_e32 v25, 0x3fb8aa3b, v21
	v_pk_add_f32 v[10:11], v[10:11], v[38:39]
	v_pk_fma_f32 v[8:9], v[8:9], v[42:43], v[40:41]
	global_load_dword v60, v[18:19], off offset:-2048
	global_load_dword v61, v[16:17], off offset:-2048
	v_exp_f32_e32 v24, v24
	v_exp_f32_e32 v25, v25
	s_waitcnt vmcnt(46)
	v_lshlrev_b32_e32 v26, 16, v78
	v_and_b32_e32 v27, 0xffff0000, v78
	v_lshlrev_b32_e32 v28, 16, v79
	v_and_b32_e32 v29, 0xffff0000, v79
	v_mul_f32_e32 v30, 0x3fb8aa3b, v26
	v_mul_f32_e32 v31, 0x3fb8aa3b, v27
	v_pk_add_f32 v[10:11], v[10:11], v[20:21]
	v_pk_fma_f32 v[8:9], v[8:9], v[24:25], v[22:23]
	global_load_dword v62, v[18:19], off offset:-1792
	global_load_dword v63, v[16:17], off offset:-1792
	v_exp_f32_e32 v30, v30
	v_exp_f32_e32 v31, v31
	s_waitcnt vmcnt(46)
	v_lshlrev_b32_e32 v32, 16, v80
	v_and_b32_e32 v33, 0xffff0000, v80
	v_lshlrev_b32_e32 v34, 16, v81
	v_and_b32_e32 v35, 0xffff0000, v81
	v_mul_f32_e32 v36, 0x3fb8aa3b, v32
	v_mul_f32_e32 v37, 0x3fb8aa3b, v33
	v_pk_add_f32 v[10:11], v[10:11], v[26:27]
	v_pk_fma_f32 v[8:9], v[8:9], v[30:31], v[28:29]
	global_load_dword v64, v[18:19], off offset:-1536
	global_load_dword v65, v[16:17], off offset:-1536
	v_exp_f32_e32 v36, v36
	v_exp_f32_e32 v37, v37
	s_waitcnt vmcnt(46)
	v_lshlrev_b32_e32 v38, 16, v82
	v_and_b32_e32 v39, 0xffff0000, v82
	v_lshlrev_b32_e32 v40, 16, v83
	v_and_b32_e32 v41, 0xffff0000, v83
	v_mul_f32_e32 v42, 0x3fb8aa3b, v38
	v_mul_f32_e32 v43, 0x3fb8aa3b, v39
	v_pk_add_f32 v[10:11], v[10:11], v[32:33]
	v_pk_fma_f32 v[8:9], v[8:9], v[36:37], v[34:35]
	global_load_dword v66, v[18:19], off offset:-1280
	global_load_dword v67, v[16:17], off offset:-1280
	v_exp_f32_e32 v42, v42
	v_exp_f32_e32 v43, v43
	s_waitcnt vmcnt(46)
	v_lshlrev_b32_e32 v20, 16, v84
	v_and_b32_e32 v21, 0xffff0000, v84
	v_lshlrev_b32_e32 v22, 16, v85
	v_and_b32_e32 v23, 0xffff0000, v85
	v_mul_f32_e32 v24, 0x3fb8aa3b, v20
	v_mul_f32_e32 v25, 0x3fb8aa3b, v21
	v_pk_add_f32 v[10:11], v[10:11], v[38:39]
	v_pk_fma_f32 v[8:9], v[8:9], v[42:43], v[40:41]
	global_load_dword v68, v[18:19], off offset:-1024
	global_load_dword v69, v[16:17], off offset:-1024
	v_exp_f32_e32 v24, v24
	v_exp_f32_e32 v25, v25
	s_waitcnt vmcnt(46)
	v_lshlrev_b32_e32 v26, 16, v86
	v_and_b32_e32 v27, 0xffff0000, v86
	v_lshlrev_b32_e32 v28, 16, v87
	v_and_b32_e32 v29, 0xffff0000, v87
	v_mul_f32_e32 v30, 0x3fb8aa3b, v26
	v_mul_f32_e32 v31, 0x3fb8aa3b, v27
	v_pk_add_f32 v[10:11], v[10:11], v[20:21]
	v_pk_fma_f32 v[8:9], v[8:9], v[24:25], v[22:23]
	global_load_dword v70, v[18:19], off offset:-768
	global_load_dword v71, v[16:17], off offset:-768
	v_exp_f32_e32 v30, v30
	v_exp_f32_e32 v31, v31
	s_waitcnt vmcnt(46)
	v_lshlrev_b32_e32 v32, 16, v88
	v_and_b32_e32 v33, 0xffff0000, v88
	v_lshlrev_b32_e32 v34, 16, v89
	v_and_b32_e32 v35, 0xffff0000, v89
	v_mul_f32_e32 v36, 0x3fb8aa3b, v32
	v_mul_f32_e32 v37, 0x3fb8aa3b, v33
	v_pk_add_f32 v[10:11], v[10:11], v[26:27]
	v_pk_fma_f32 v[8:9], v[8:9], v[30:31], v[28:29]
	global_load_dword v72, v[18:19], off offset:-512
	global_load_dword v73, v[16:17], off offset:-512
	v_exp_f32_e32 v36, v36
	v_exp_f32_e32 v37, v37
	s_waitcnt vmcnt(46)
	v_lshlrev_b32_e32 v38, 16, v90
	v_and_b32_e32 v39, 0xffff0000, v90
	v_lshlrev_b32_e32 v40, 16, v91
	v_and_b32_e32 v41, 0xffff0000, v91
	v_mul_f32_e32 v42, 0x3fb8aa3b, v38
	v_mul_f32_e32 v43, 0x3fb8aa3b, v39
	v_pk_add_f32 v[10:11], v[10:11], v[32:33]
	v_pk_fma_f32 v[8:9], v[8:9], v[36:37], v[34:35]
	global_load_dword v74, v[18:19], off offset:-256
	global_load_dword v75, v[16:17], off offset:-256
	v_exp_f32_e32 v42, v42
	v_exp_f32_e32 v43, v43
	s_waitcnt vmcnt(46)
	v_lshlrev_b32_e32 v20, 16, v92
	v_and_b32_e32 v21, 0xffff0000, v92
	v_lshlrev_b32_e32 v22, 16, v93
	v_and_b32_e32 v23, 0xffff0000, v93
	v_mul_f32_e32 v24, 0x3fb8aa3b, v20
	v_mul_f32_e32 v25, 0x3fb8aa3b, v21
	v_pk_add_f32 v[10:11], v[10:11], v[38:39]
	v_pk_fma_f32 v[8:9], v[8:9], v[42:43], v[40:41]
	global_load_dword v76, v[18:19], off
	global_load_dword v77, v[16:17], off
	v_exp_f32_e32 v24, v24
	v_exp_f32_e32 v25, v25
	s_waitcnt vmcnt(46)
	v_lshlrev_b32_e32 v26, 16, v94
	v_and_b32_e32 v27, 0xffff0000, v94
	v_lshlrev_b32_e32 v28, 16, v95
	v_and_b32_e32 v29, 0xffff0000, v95
	v_mul_f32_e32 v30, 0x3fb8aa3b, v26
	v_mul_f32_e32 v31, 0x3fb8aa3b, v27
	v_pk_add_f32 v[10:11], v[10:11], v[20:21]
	v_pk_fma_f32 v[8:9], v[8:9], v[24:25], v[22:23]
	global_load_dword v78, v[18:19], off offset:256
	global_load_dword v79, v[16:17], off offset:256
	v_exp_f32_e32 v30, v30
	v_exp_f32_e32 v31, v31
	s_waitcnt vmcnt(46)
	v_lshlrev_b32_e32 v32, 16, v96
	v_and_b32_e32 v33, 0xffff0000, v96
	v_lshlrev_b32_e32 v34, 16, v97
	v_and_b32_e32 v35, 0xffff0000, v97
	v_mul_f32_e32 v36, 0x3fb8aa3b, v32
	v_mul_f32_e32 v37, 0x3fb8aa3b, v33
	v_pk_add_f32 v[10:11], v[10:11], v[26:27]
	v_pk_fma_f32 v[8:9], v[8:9], v[30:31], v[28:29]
	global_load_dword v80, v[18:19], off offset:512
	global_load_dword v81, v[16:17], off offset:512
	v_exp_f32_e32 v36, v36
	v_exp_f32_e32 v37, v37
	s_waitcnt vmcnt(46)
	v_lshlrev_b32_e32 v38, 16, v98
	v_and_b32_e32 v39, 0xffff0000, v98
	v_lshlrev_b32_e32 v40, 16, v99
	v_and_b32_e32 v41, 0xffff0000, v99
	v_mul_f32_e32 v42, 0x3fb8aa3b, v38
	v_mul_f32_e32 v43, 0x3fb8aa3b, v39
	v_pk_add_f32 v[10:11], v[10:11], v[32:33]
	v_pk_fma_f32 v[8:9], v[8:9], v[36:37], v[34:35]
	global_load_dword v82, v[18:19], off offset:768
	global_load_dword v83, v[16:17], off offset:768
	v_exp_f32_e32 v42, v42
	v_exp_f32_e32 v43, v43
	s_waitcnt vmcnt(46)
	v_lshlrev_b32_e32 v20, 16, v100
	v_and_b32_e32 v21, 0xffff0000, v100
	v_lshlrev_b32_e32 v22, 16, v101
	v_and_b32_e32 v23, 0xffff0000, v101
	v_mul_f32_e32 v24, 0x3fb8aa3b, v20
	v_mul_f32_e32 v25, 0x3fb8aa3b, v21
	v_pk_add_f32 v[10:11], v[10:11], v[38:39]
	v_pk_fma_f32 v[8:9], v[8:9], v[42:43], v[40:41]
	global_load_dword v84, v[18:19], off offset:1024
	global_load_dword v85, v[16:17], off offset:1024
	v_exp_f32_e32 v24, v24
	v_exp_f32_e32 v25, v25
	s_waitcnt vmcnt(46)
	v_lshlrev_b32_e32 v26, 16, v102
	v_and_b32_e32 v27, 0xffff0000, v102
	v_lshlrev_b32_e32 v28, 16, v103
	v_and_b32_e32 v29, 0xffff0000, v103
	v_mul_f32_e32 v30, 0x3fb8aa3b, v26
	v_mul_f32_e32 v31, 0x3fb8aa3b, v27
	v_pk_add_f32 v[10:11], v[10:11], v[20:21]
	v_pk_fma_f32 v[8:9], v[8:9], v[24:25], v[22:23]
	global_load_dword v86, v[18:19], off offset:1280
	global_load_dword v87, v[16:17], off offset:1280
	v_exp_f32_e32 v30, v30
	v_exp_f32_e32 v31, v31
	s_waitcnt vmcnt(46)
	v_lshlrev_b32_e32 v32, 16, v104
	v_and_b32_e32 v33, 0xffff0000, v104
	v_lshlrev_b32_e32 v34, 16, v105
	v_and_b32_e32 v35, 0xffff0000, v105
	v_mul_f32_e32 v36, 0x3fb8aa3b, v32
	v_mul_f32_e32 v37, 0x3fb8aa3b, v33
	v_pk_add_f32 v[10:11], v[10:11], v[26:27]
	v_pk_fma_f32 v[8:9], v[8:9], v[30:31], v[28:29]
	global_load_dword v88, v[18:19], off offset:1536
	global_load_dword v89, v[16:17], off offset:1536
	v_exp_f32_e32 v36, v36
	v_exp_f32_e32 v37, v37
	s_waitcnt vmcnt(46)
	v_lshlrev_b32_e32 v38, 16, v106
	v_and_b32_e32 v39, 0xffff0000, v106
	v_lshlrev_b32_e32 v40, 16, v107
	v_and_b32_e32 v41, 0xffff0000, v107
	v_mul_f32_e32 v42, 0x3fb8aa3b, v38
	v_mul_f32_e32 v43, 0x3fb8aa3b, v39
	v_pk_add_f32 v[10:11], v[10:11], v[32:33]
	v_pk_fma_f32 v[8:9], v[8:9], v[36:37], v[34:35]
	global_load_dword v90, v[18:19], off offset:1792
	global_load_dword v91, v[16:17], off offset:1792
	v_exp_f32_e32 v42, v42
	v_exp_f32_e32 v43, v43
	s_waitcnt vmcnt(46)
	v_lshlrev_b32_e32 v20, 16, v44
	v_and_b32_e32 v21, 0xffff0000, v44
	v_lshlrev_b32_e32 v22, 16, v45
	v_and_b32_e32 v23, 0xffff0000, v45
	v_mul_f32_e32 v24, 0x3fb8aa3b, v20
	v_mul_f32_e32 v25, 0x3fb8aa3b, v21
	v_pk_add_f32 v[10:11], v[10:11], v[38:39]
	v_pk_fma_f32 v[8:9], v[8:9], v[42:43], v[40:41]
	global_load_dword v92, v[18:19], off offset:2048
	global_load_dword v93, v[16:17], off offset:2048
	v_exp_f32_e32 v24, v24
	v_exp_f32_e32 v25, v25
	s_waitcnt vmcnt(46)
	v_lshlrev_b32_e32 v26, 16, v46
	v_and_b32_e32 v27, 0xffff0000, v46
	v_lshlrev_b32_e32 v28, 16, v47
	v_and_b32_e32 v29, 0xffff0000, v47
	v_mul_f32_e32 v30, 0x3fb8aa3b, v26
	v_mul_f32_e32 v31, 0x3fb8aa3b, v27
	v_pk_add_f32 v[10:11], v[10:11], v[20:21]
	v_pk_fma_f32 v[8:9], v[8:9], v[24:25], v[22:23]
	global_load_dword v94, v[18:19], off offset:2304
	global_load_dword v95, v[16:17], off offset:2304
	v_exp_f32_e32 v30, v30
	v_exp_f32_e32 v31, v31
	s_waitcnt vmcnt(46)
	v_lshlrev_b32_e32 v32, 16, v48
	v_and_b32_e32 v33, 0xffff0000, v48
	v_lshlrev_b32_e32 v34, 16, v49
	v_and_b32_e32 v35, 0xffff0000, v49
	v_mul_f32_e32 v36, 0x3fb8aa3b, v32
	v_mul_f32_e32 v37, 0x3fb8aa3b, v33
	v_pk_add_f32 v[10:11], v[10:11], v[26:27]
	v_pk_fma_f32 v[8:9], v[8:9], v[30:31], v[28:29]
	global_load_dword v96, v[18:19], off offset:2560
	global_load_dword v97, v[16:17], off offset:2560
	v_exp_f32_e32 v36, v36
	v_exp_f32_e32 v37, v37
	s_waitcnt vmcnt(46)
	v_lshlrev_b32_e32 v38, 16, v50
	v_and_b32_e32 v39, 0xffff0000, v50
	v_lshlrev_b32_e32 v40, 16, v51
	v_and_b32_e32 v41, 0xffff0000, v51
	v_mul_f32_e32 v42, 0x3fb8aa3b, v38
	v_mul_f32_e32 v43, 0x3fb8aa3b, v39
	v_pk_add_f32 v[10:11], v[10:11], v[32:33]
	v_pk_fma_f32 v[8:9], v[8:9], v[36:37], v[34:35]
	global_load_dword v98, v[18:19], off offset:2816
	global_load_dword v99, v[16:17], off offset:2816
	v_exp_f32_e32 v42, v42
	v_exp_f32_e32 v43, v43
	s_waitcnt vmcnt(46)
	v_lshlrev_b32_e32 v20, 16, v52
	v_and_b32_e32 v21, 0xffff0000, v52
	v_lshlrev_b32_e32 v22, 16, v53
	v_and_b32_e32 v23, 0xffff0000, v53
	v_mul_f32_e32 v24, 0x3fb8aa3b, v20
	v_mul_f32_e32 v25, 0x3fb8aa3b, v21
	v_pk_add_f32 v[10:11], v[10:11], v[38:39]
	v_pk_fma_f32 v[8:9], v[8:9], v[42:43], v[40:41]
	global_load_dword v100, v[18:19], off offset:3072
	global_load_dword v101, v[16:17], off offset:3072
	v_exp_f32_e32 v24, v24
	v_exp_f32_e32 v25, v25
	s_waitcnt vmcnt(46)
	v_lshlrev_b32_e32 v26, 16, v54
	v_and_b32_e32 v27, 0xffff0000, v54
	v_lshlrev_b32_e32 v28, 16, v55
	v_and_b32_e32 v29, 0xffff0000, v55
	v_mul_f32_e32 v30, 0x3fb8aa3b, v26
	v_mul_f32_e32 v31, 0x3fb8aa3b, v27
	v_pk_add_f32 v[10:11], v[10:11], v[20:21]
	v_pk_fma_f32 v[8:9], v[8:9], v[24:25], v[22:23]
	global_load_dword v102, v[18:19], off offset:3328
	global_load_dword v103, v[16:17], off offset:3328
	v_exp_f32_e32 v30, v30
	v_exp_f32_e32 v31, v31
	s_waitcnt vmcnt(46)
	v_lshlrev_b32_e32 v32, 16, v56
	v_and_b32_e32 v33, 0xffff0000, v56
	v_lshlrev_b32_e32 v34, 16, v57
	v_and_b32_e32 v35, 0xffff0000, v57
	v_mul_f32_e32 v36, 0x3fb8aa3b, v32
	v_mul_f32_e32 v37, 0x3fb8aa3b, v33
	v_pk_add_f32 v[10:11], v[10:11], v[26:27]
	v_pk_fma_f32 v[8:9], v[8:9], v[30:31], v[28:29]
	global_load_dword v104, v[18:19], off offset:3584
	global_load_dword v105, v[16:17], off offset:3584
	v_exp_f32_e32 v36, v36
	v_exp_f32_e32 v37, v37
	s_waitcnt vmcnt(46)
	v_lshlrev_b32_e32 v38, 16, v58
	v_and_b32_e32 v39, 0xffff0000, v58
	v_lshlrev_b32_e32 v40, 16, v59
	v_and_b32_e32 v41, 0xffff0000, v59
	v_mul_f32_e32 v42, 0x3fb8aa3b, v38
	v_mul_f32_e32 v43, 0x3fb8aa3b, v39
	v_pk_add_f32 v[10:11], v[10:11], v[32:33]
	v_pk_fma_f32 v[8:9], v[8:9], v[36:37], v[34:35]
	global_load_dword v106, v[18:19], off offset:3840
	global_load_dword v107, v[16:17], off offset:3840
	v_exp_f32_e32 v42, v42
	v_exp_f32_e32 v43, v43
	s_waitcnt vmcnt(46)
	v_lshlrev_b32_e32 v20, 16, v60
	v_and_b32_e32 v21, 0xffff0000, v60
	v_lshlrev_b32_e32 v22, 16, v61
	v_and_b32_e32 v23, 0xffff0000, v61
	v_mul_f32_e32 v24, 0x3fb8aa3b, v20
	v_mul_f32_e32 v25, 0x3fb8aa3b, v21
	v_pk_add_f32 v[10:11], v[10:11], v[38:39]
	v_pk_fma_f32 v[8:9], v[8:9], v[42:43], v[40:41]
	v_lshl_add_u64 v[18:19], v[18:19], 0, s[0:1]
	v_lshl_add_u64 v[18:19], v[18:19], 0, s[0:1]
	v_lshl_add_u64 v[16:17], v[16:17], 0, s[0:1]
	v_lshl_add_u64 v[16:17], v[16:17], 0, s[0:1]
	global_load_dword v44, v[18:19], off offset:-4096
	global_load_dword v45, v[16:17], off offset:-4096
	v_exp_f32_e32 v24, v24
	v_exp_f32_e32 v25, v25
	s_waitcnt vmcnt(46)
	v_lshlrev_b32_e32 v26, 16, v62
	v_and_b32_e32 v27, 0xffff0000, v62
	v_lshlrev_b32_e32 v28, 16, v63
	v_and_b32_e32 v29, 0xffff0000, v63
	v_mul_f32_e32 v30, 0x3fb8aa3b, v26
	v_mul_f32_e32 v31, 0x3fb8aa3b, v27
	v_pk_add_f32 v[10:11], v[10:11], v[20:21]
	v_pk_fma_f32 v[8:9], v[8:9], v[24:25], v[22:23]
	global_load_dword v46, v[18:19], off offset:-3840
	global_load_dword v47, v[16:17], off offset:-3840
	v_exp_f32_e32 v30, v30
	v_exp_f32_e32 v31, v31
	s_waitcnt vmcnt(46)
	v_lshlrev_b32_e32 v32, 16, v64
	v_and_b32_e32 v33, 0xffff0000, v64
	v_lshlrev_b32_e32 v34, 16, v65
	v_and_b32_e32 v35, 0xffff0000, v65
	v_mul_f32_e32 v36, 0x3fb8aa3b, v32
	v_mul_f32_e32 v37, 0x3fb8aa3b, v33
	v_pk_add_f32 v[10:11], v[10:11], v[26:27]
	v_pk_fma_f32 v[8:9], v[8:9], v[30:31], v[28:29]
	global_load_dword v48, v[18:19], off offset:-3584
	global_load_dword v49, v[16:17], off offset:-3584
	v_exp_f32_e32 v36, v36
	v_exp_f32_e32 v37, v37
	s_waitcnt vmcnt(46)
	v_lshlrev_b32_e32 v38, 16, v66
	v_and_b32_e32 v39, 0xffff0000, v66
	v_lshlrev_b32_e32 v40, 16, v67
	v_and_b32_e32 v41, 0xffff0000, v67
	v_mul_f32_e32 v42, 0x3fb8aa3b, v38
	v_mul_f32_e32 v43, 0x3fb8aa3b, v39
	v_pk_add_f32 v[10:11], v[10:11], v[32:33]
	v_pk_fma_f32 v[8:9], v[8:9], v[36:37], v[34:35]
	global_load_dword v50, v[18:19], off offset:-3328
	global_load_dword v51, v[16:17], off offset:-3328
	v_exp_f32_e32 v42, v42
	v_exp_f32_e32 v43, v43
	s_waitcnt vmcnt(46)
	v_lshlrev_b32_e32 v20, 16, v68
	v_and_b32_e32 v21, 0xffff0000, v68
	v_lshlrev_b32_e32 v22, 16, v69
	v_and_b32_e32 v23, 0xffff0000, v69
	v_mul_f32_e32 v24, 0x3fb8aa3b, v20
	v_mul_f32_e32 v25, 0x3fb8aa3b, v21
	v_pk_add_f32 v[10:11], v[10:11], v[38:39]
	v_pk_fma_f32 v[8:9], v[8:9], v[42:43], v[40:41]
	global_load_dword v52, v[18:19], off offset:-3072
	global_load_dword v53, v[16:17], off offset:-3072
	v_exp_f32_e32 v24, v24
	v_exp_f32_e32 v25, v25
	s_waitcnt vmcnt(46)
	v_lshlrev_b32_e32 v26, 16, v70
	v_and_b32_e32 v27, 0xffff0000, v70
	v_lshlrev_b32_e32 v28, 16, v71
	v_and_b32_e32 v29, 0xffff0000, v71
	v_mul_f32_e32 v30, 0x3fb8aa3b, v26
	v_mul_f32_e32 v31, 0x3fb8aa3b, v27
	v_pk_add_f32 v[10:11], v[10:11], v[20:21]
	v_pk_fma_f32 v[8:9], v[8:9], v[24:25], v[22:23]
	global_load_dword v54, v[18:19], off offset:-2816
	global_load_dword v55, v[16:17], off offset:-2816
	v_exp_f32_e32 v30, v30
	v_exp_f32_e32 v31, v31
	s_waitcnt vmcnt(46)
	v_lshlrev_b32_e32 v32, 16, v72
	v_and_b32_e32 v33, 0xffff0000, v72
	v_lshlrev_b32_e32 v34, 16, v73
	v_and_b32_e32 v35, 0xffff0000, v73
	v_mul_f32_e32 v36, 0x3fb8aa3b, v32
	v_mul_f32_e32 v37, 0x3fb8aa3b, v33
	v_pk_add_f32 v[10:11], v[10:11], v[26:27]
	v_pk_fma_f32 v[8:9], v[8:9], v[30:31], v[28:29]
	global_load_dword v56, v[18:19], off offset:-2560
	global_load_dword v57, v[16:17], off offset:-2560
	v_exp_f32_e32 v36, v36
	v_exp_f32_e32 v37, v37
	s_waitcnt vmcnt(46)
	v_lshlrev_b32_e32 v38, 16, v74
	v_and_b32_e32 v39, 0xffff0000, v74
	v_lshlrev_b32_e32 v40, 16, v75
	v_and_b32_e32 v41, 0xffff0000, v75
	v_mul_f32_e32 v42, 0x3fb8aa3b, v38
	v_mul_f32_e32 v43, 0x3fb8aa3b, v39
	v_pk_add_f32 v[10:11], v[10:11], v[32:33]
	v_pk_fma_f32 v[8:9], v[8:9], v[36:37], v[34:35]
	global_load_dword v58, v[18:19], off offset:-2304
	global_load_dword v59, v[16:17], off offset:-2304
	v_exp_f32_e32 v42, v42
	v_exp_f32_e32 v43, v43
	s_waitcnt vmcnt(46)
	v_lshlrev_b32_e32 v20, 16, v76
	v_and_b32_e32 v21, 0xffff0000, v76
	v_lshlrev_b32_e32 v22, 16, v77
	v_and_b32_e32 v23, 0xffff0000, v77
	v_mul_f32_e32 v24, 0x3fb8aa3b, v20
	v_mul_f32_e32 v25, 0x3fb8aa3b, v21
	v_pk_add_f32 v[10:11], v[10:11], v[38:39]
	v_pk_fma_f32 v[8:9], v[8:9], v[42:43], v[40:41]
	global_load_dword v60, v[18:19], off offset:-2048
	global_load_dword v61, v[16:17], off offset:-2048
	v_exp_f32_e32 v24, v24
	v_exp_f32_e32 v25, v25
	s_waitcnt vmcnt(46)
	v_lshlrev_b32_e32 v26, 16, v78
	v_and_b32_e32 v27, 0xffff0000, v78
	v_lshlrev_b32_e32 v28, 16, v79
	v_and_b32_e32 v29, 0xffff0000, v79
	v_mul_f32_e32 v30, 0x3fb8aa3b, v26
	v_mul_f32_e32 v31, 0x3fb8aa3b, v27
	v_pk_add_f32 v[10:11], v[10:11], v[20:21]
	v_pk_fma_f32 v[8:9], v[8:9], v[24:25], v[22:23]
	global_load_dword v62, v[18:19], off offset:-1792
	global_load_dword v63, v[16:17], off offset:-1792
	v_exp_f32_e32 v30, v30
	v_exp_f32_e32 v31, v31
	s_waitcnt vmcnt(46)
	v_lshlrev_b32_e32 v32, 16, v80
	v_and_b32_e32 v33, 0xffff0000, v80
	v_lshlrev_b32_e32 v34, 16, v81
	v_and_b32_e32 v35, 0xffff0000, v81
	v_mul_f32_e32 v36, 0x3fb8aa3b, v32
	v_mul_f32_e32 v37, 0x3fb8aa3b, v33
	v_pk_add_f32 v[10:11], v[10:11], v[26:27]
	v_pk_fma_f32 v[8:9], v[8:9], v[30:31], v[28:29]
	global_load_dword v64, v[18:19], off offset:-1536
	global_load_dword v65, v[16:17], off offset:-1536
	v_exp_f32_e32 v36, v36
	v_exp_f32_e32 v37, v37
	s_waitcnt vmcnt(46)
	v_lshlrev_b32_e32 v38, 16, v82
	v_and_b32_e32 v39, 0xffff0000, v82
	v_lshlrev_b32_e32 v40, 16, v83
	v_and_b32_e32 v41, 0xffff0000, v83
	v_mul_f32_e32 v42, 0x3fb8aa3b, v38
	v_mul_f32_e32 v43, 0x3fb8aa3b, v39
	v_pk_add_f32 v[10:11], v[10:11], v[32:33]
	v_pk_fma_f32 v[8:9], v[8:9], v[36:37], v[34:35]
	global_load_dword v66, v[18:19], off offset:-1280
	global_load_dword v67, v[16:17], off offset:-1280
	v_exp_f32_e32 v42, v42
	v_exp_f32_e32 v43, v43
	s_waitcnt vmcnt(46)
	v_lshlrev_b32_e32 v20, 16, v84
	v_and_b32_e32 v21, 0xffff0000, v84
	v_lshlrev_b32_e32 v22, 16, v85
	v_and_b32_e32 v23, 0xffff0000, v85
	v_mul_f32_e32 v24, 0x3fb8aa3b, v20
	v_mul_f32_e32 v25, 0x3fb8aa3b, v21
	v_pk_add_f32 v[10:11], v[10:11], v[38:39]
	v_pk_fma_f32 v[8:9], v[8:9], v[42:43], v[40:41]
	global_load_dword v68, v[18:19], off offset:-1024
	global_load_dword v69, v[16:17], off offset:-1024
	v_exp_f32_e32 v24, v24
	v_exp_f32_e32 v25, v25
	s_waitcnt vmcnt(46)
	v_lshlrev_b32_e32 v26, 16, v86
	v_and_b32_e32 v27, 0xffff0000, v86
	v_lshlrev_b32_e32 v28, 16, v87
	v_and_b32_e32 v29, 0xffff0000, v87
	v_mul_f32_e32 v30, 0x3fb8aa3b, v26
	v_mul_f32_e32 v31, 0x3fb8aa3b, v27
	v_pk_add_f32 v[10:11], v[10:11], v[20:21]
	v_pk_fma_f32 v[8:9], v[8:9], v[24:25], v[22:23]
	global_load_dword v70, v[18:19], off offset:-768
	global_load_dword v71, v[16:17], off offset:-768
	v_exp_f32_e32 v30, v30
	v_exp_f32_e32 v31, v31
	s_waitcnt vmcnt(46)
	v_lshlrev_b32_e32 v32, 16, v88
	v_and_b32_e32 v33, 0xffff0000, v88
	v_lshlrev_b32_e32 v34, 16, v89
	v_and_b32_e32 v35, 0xffff0000, v89
	v_mul_f32_e32 v36, 0x3fb8aa3b, v32
	v_mul_f32_e32 v37, 0x3fb8aa3b, v33
	v_pk_add_f32 v[10:11], v[10:11], v[26:27]
	v_pk_fma_f32 v[8:9], v[8:9], v[30:31], v[28:29]
	global_load_dword v72, v[18:19], off offset:-512
	global_load_dword v73, v[16:17], off offset:-512
	v_exp_f32_e32 v36, v36
	v_exp_f32_e32 v37, v37
	s_waitcnt vmcnt(46)
	v_lshlrev_b32_e32 v38, 16, v90
	v_and_b32_e32 v39, 0xffff0000, v90
	v_lshlrev_b32_e32 v40, 16, v91
	v_and_b32_e32 v41, 0xffff0000, v91
	v_mul_f32_e32 v42, 0x3fb8aa3b, v38
	v_mul_f32_e32 v43, 0x3fb8aa3b, v39
	v_pk_add_f32 v[10:11], v[10:11], v[32:33]
	v_pk_fma_f32 v[8:9], v[8:9], v[36:37], v[34:35]
	global_load_dword v74, v[18:19], off offset:-256
	global_load_dword v75, v[16:17], off offset:-256
	v_exp_f32_e32 v42, v42
	v_exp_f32_e32 v43, v43
	s_waitcnt vmcnt(46)
	v_lshlrev_b32_e32 v20, 16, v92
	v_and_b32_e32 v21, 0xffff0000, v92
	v_lshlrev_b32_e32 v22, 16, v93
	v_and_b32_e32 v23, 0xffff0000, v93
	v_mul_f32_e32 v24, 0x3fb8aa3b, v20
	v_mul_f32_e32 v25, 0x3fb8aa3b, v21
	v_pk_add_f32 v[10:11], v[10:11], v[38:39]
	v_pk_fma_f32 v[8:9], v[8:9], v[42:43], v[40:41]
	global_load_dword v76, v[18:19], off
	global_load_dword v77, v[16:17], off
	v_exp_f32_e32 v24, v24
	v_exp_f32_e32 v25, v25
	s_waitcnt vmcnt(46)
	v_lshlrev_b32_e32 v26, 16, v94
	v_and_b32_e32 v27, 0xffff0000, v94
	v_lshlrev_b32_e32 v28, 16, v95
	v_and_b32_e32 v29, 0xffff0000, v95
	v_mul_f32_e32 v30, 0x3fb8aa3b, v26
	v_mul_f32_e32 v31, 0x3fb8aa3b, v27
	v_pk_add_f32 v[10:11], v[10:11], v[20:21]
	v_pk_fma_f32 v[8:9], v[8:9], v[24:25], v[22:23]
	global_load_dword v78, v[18:19], off offset:256
	global_load_dword v79, v[16:17], off offset:256
	v_exp_f32_e32 v30, v30
	v_exp_f32_e32 v31, v31
	s_waitcnt vmcnt(46)
	v_lshlrev_b32_e32 v32, 16, v96
	v_and_b32_e32 v33, 0xffff0000, v96
	v_lshlrev_b32_e32 v34, 16, v97
	v_and_b32_e32 v35, 0xffff0000, v97
	v_mul_f32_e32 v36, 0x3fb8aa3b, v32
	v_mul_f32_e32 v37, 0x3fb8aa3b, v33
	v_pk_add_f32 v[10:11], v[10:11], v[26:27]
	v_pk_fma_f32 v[8:9], v[8:9], v[30:31], v[28:29]
	global_load_dword v80, v[18:19], off offset:512
	global_load_dword v81, v[16:17], off offset:512
	v_exp_f32_e32 v36, v36
	v_exp_f32_e32 v37, v37
	s_waitcnt vmcnt(46)
	v_lshlrev_b32_e32 v38, 16, v98
	v_and_b32_e32 v39, 0xffff0000, v98
	v_lshlrev_b32_e32 v40, 16, v99
	v_and_b32_e32 v41, 0xffff0000, v99
	v_mul_f32_e32 v42, 0x3fb8aa3b, v38
	v_mul_f32_e32 v43, 0x3fb8aa3b, v39
	v_pk_add_f32 v[10:11], v[10:11], v[32:33]
	v_pk_fma_f32 v[8:9], v[8:9], v[36:37], v[34:35]
	global_load_dword v82, v[18:19], off offset:768
	global_load_dword v83, v[16:17], off offset:768
	v_exp_f32_e32 v42, v42
	v_exp_f32_e32 v43, v43
	s_waitcnt vmcnt(46)
	v_lshlrev_b32_e32 v20, 16, v100
	v_and_b32_e32 v21, 0xffff0000, v100
	v_lshlrev_b32_e32 v22, 16, v101
	v_and_b32_e32 v23, 0xffff0000, v101
	v_mul_f32_e32 v24, 0x3fb8aa3b, v20
	v_mul_f32_e32 v25, 0x3fb8aa3b, v21
	v_pk_add_f32 v[10:11], v[10:11], v[38:39]
	v_pk_fma_f32 v[8:9], v[8:9], v[42:43], v[40:41]
	global_load_dword v84, v[18:19], off offset:1024
	global_load_dword v85, v[16:17], off offset:1024
	v_exp_f32_e32 v24, v24
	v_exp_f32_e32 v25, v25
	s_waitcnt vmcnt(46)
	v_lshlrev_b32_e32 v26, 16, v102
	v_and_b32_e32 v27, 0xffff0000, v102
	v_lshlrev_b32_e32 v28, 16, v103
	v_and_b32_e32 v29, 0xffff0000, v103
	v_mul_f32_e32 v30, 0x3fb8aa3b, v26
	v_mul_f32_e32 v31, 0x3fb8aa3b, v27
	v_pk_add_f32 v[10:11], v[10:11], v[20:21]
	v_pk_fma_f32 v[8:9], v[8:9], v[24:25], v[22:23]
	global_load_dword v86, v[18:19], off offset:1280
	global_load_dword v87, v[16:17], off offset:1280
	v_exp_f32_e32 v30, v30
	v_exp_f32_e32 v31, v31
	s_waitcnt vmcnt(46)
	v_lshlrev_b32_e32 v32, 16, v104
	v_and_b32_e32 v33, 0xffff0000, v104
	v_lshlrev_b32_e32 v34, 16, v105
	v_and_b32_e32 v35, 0xffff0000, v105
	v_mul_f32_e32 v36, 0x3fb8aa3b, v32
	v_mul_f32_e32 v37, 0x3fb8aa3b, v33
	v_pk_add_f32 v[10:11], v[10:11], v[26:27]
	v_pk_fma_f32 v[8:9], v[8:9], v[30:31], v[28:29]
	global_load_dword v88, v[18:19], off offset:1536
	global_load_dword v89, v[16:17], off offset:1536
	v_exp_f32_e32 v36, v36
	v_exp_f32_e32 v37, v37
	s_waitcnt vmcnt(46)
	v_lshlrev_b32_e32 v38, 16, v106
	v_and_b32_e32 v39, 0xffff0000, v106
	v_lshlrev_b32_e32 v40, 16, v107
	v_and_b32_e32 v41, 0xffff0000, v107
	v_mul_f32_e32 v42, 0x3fb8aa3b, v38
	v_mul_f32_e32 v43, 0x3fb8aa3b, v39
	v_pk_add_f32 v[10:11], v[10:11], v[32:33]
	v_pk_fma_f32 v[8:9], v[8:9], v[36:37], v[34:35]
	global_load_dword v90, v[18:19], off offset:1792
	global_load_dword v91, v[16:17], off offset:1792
	v_exp_f32_e32 v42, v42
	v_exp_f32_e32 v43, v43
	s_waitcnt vmcnt(46)
	v_lshlrev_b32_e32 v20, 16, v44
	v_and_b32_e32 v21, 0xffff0000, v44
	v_lshlrev_b32_e32 v22, 16, v45
	v_and_b32_e32 v23, 0xffff0000, v45
	v_mul_f32_e32 v24, 0x3fb8aa3b, v20
	v_mul_f32_e32 v25, 0x3fb8aa3b, v21
	v_pk_add_f32 v[10:11], v[10:11], v[38:39]
	v_pk_fma_f32 v[8:9], v[8:9], v[42:43], v[40:41]
	global_load_dword v92, v[18:19], off offset:2048
	global_load_dword v93, v[16:17], off offset:2048
	v_exp_f32_e32 v24, v24
	v_exp_f32_e32 v25, v25
	s_waitcnt vmcnt(46)
	v_lshlrev_b32_e32 v26, 16, v46
	v_and_b32_e32 v27, 0xffff0000, v46
	v_lshlrev_b32_e32 v28, 16, v47
	v_and_b32_e32 v29, 0xffff0000, v47
	v_mul_f32_e32 v30, 0x3fb8aa3b, v26
	v_mul_f32_e32 v31, 0x3fb8aa3b, v27
	v_pk_add_f32 v[10:11], v[10:11], v[20:21]
	v_pk_fma_f32 v[8:9], v[8:9], v[24:25], v[22:23]
	global_load_dword v94, v[18:19], off offset:2304
	global_load_dword v95, v[16:17], off offset:2304
	v_exp_f32_e32 v30, v30
	v_exp_f32_e32 v31, v31
	s_waitcnt vmcnt(46)
	v_lshlrev_b32_e32 v32, 16, v48
	v_and_b32_e32 v33, 0xffff0000, v48
	v_lshlrev_b32_e32 v34, 16, v49
	v_and_b32_e32 v35, 0xffff0000, v49
	v_mul_f32_e32 v36, 0x3fb8aa3b, v32
	v_mul_f32_e32 v37, 0x3fb8aa3b, v33
	v_pk_add_f32 v[10:11], v[10:11], v[26:27]
	v_pk_fma_f32 v[8:9], v[8:9], v[30:31], v[28:29]
	global_load_dword v96, v[18:19], off offset:2560
	global_load_dword v97, v[16:17], off offset:2560
	v_exp_f32_e32 v36, v36
	v_exp_f32_e32 v37, v37
	s_waitcnt vmcnt(46)
	v_lshlrev_b32_e32 v38, 16, v50
	v_and_b32_e32 v39, 0xffff0000, v50
	v_lshlrev_b32_e32 v40, 16, v51
	v_and_b32_e32 v41, 0xffff0000, v51
	v_mul_f32_e32 v42, 0x3fb8aa3b, v38
	v_mul_f32_e32 v43, 0x3fb8aa3b, v39
	v_pk_add_f32 v[10:11], v[10:11], v[32:33]
	v_pk_fma_f32 v[8:9], v[8:9], v[36:37], v[34:35]
	global_load_dword v98, v[18:19], off offset:2816
	global_load_dword v99, v[16:17], off offset:2816
	v_exp_f32_e32 v42, v42
	v_exp_f32_e32 v43, v43
	s_waitcnt vmcnt(46)
	v_lshlrev_b32_e32 v20, 16, v52
	v_and_b32_e32 v21, 0xffff0000, v52
	v_lshlrev_b32_e32 v22, 16, v53
	v_and_b32_e32 v23, 0xffff0000, v53
	v_mul_f32_e32 v24, 0x3fb8aa3b, v20
	v_mul_f32_e32 v25, 0x3fb8aa3b, v21
	v_pk_add_f32 v[10:11], v[10:11], v[38:39]
	v_pk_fma_f32 v[8:9], v[8:9], v[42:43], v[40:41]
	global_load_dword v100, v[18:19], off offset:3072
	global_load_dword v101, v[16:17], off offset:3072
	v_exp_f32_e32 v24, v24
	v_exp_f32_e32 v25, v25
	s_waitcnt vmcnt(46)
	v_lshlrev_b32_e32 v26, 16, v54
	v_and_b32_e32 v27, 0xffff0000, v54
	v_lshlrev_b32_e32 v28, 16, v55
	v_and_b32_e32 v29, 0xffff0000, v55
	v_mul_f32_e32 v30, 0x3fb8aa3b, v26
	v_mul_f32_e32 v31, 0x3fb8aa3b, v27
	v_pk_add_f32 v[10:11], v[10:11], v[20:21]
	v_pk_fma_f32 v[8:9], v[8:9], v[24:25], v[22:23]
	global_load_dword v102, v[18:19], off offset:3328
	global_load_dword v103, v[16:17], off offset:3328
	v_exp_f32_e32 v30, v30
	v_exp_f32_e32 v31, v31
	s_waitcnt vmcnt(46)
	v_lshlrev_b32_e32 v32, 16, v56
	v_and_b32_e32 v33, 0xffff0000, v56
	v_lshlrev_b32_e32 v34, 16, v57
	v_and_b32_e32 v35, 0xffff0000, v57
	v_mul_f32_e32 v36, 0x3fb8aa3b, v32
	v_mul_f32_e32 v37, 0x3fb8aa3b, v33
	v_pk_add_f32 v[10:11], v[10:11], v[26:27]
	v_pk_fma_f32 v[8:9], v[8:9], v[30:31], v[28:29]
	global_load_dword v104, v[18:19], off offset:3584
	global_load_dword v105, v[16:17], off offset:3584
	v_exp_f32_e32 v36, v36
	v_exp_f32_e32 v37, v37
	s_waitcnt vmcnt(46)
	v_lshlrev_b32_e32 v38, 16, v58
	v_and_b32_e32 v39, 0xffff0000, v58
	v_lshlrev_b32_e32 v40, 16, v59
	v_and_b32_e32 v41, 0xffff0000, v59
	v_mul_f32_e32 v42, 0x3fb8aa3b, v38
	v_mul_f32_e32 v43, 0x3fb8aa3b, v39
	v_pk_add_f32 v[10:11], v[10:11], v[32:33]
	v_pk_fma_f32 v[8:9], v[8:9], v[36:37], v[34:35]
	global_load_dword v106, v[18:19], off offset:3840
	global_load_dword v107, v[16:17], off offset:3840
	v_exp_f32_e32 v42, v42
	v_exp_f32_e32 v43, v43
	s_waitcnt vmcnt(46)
	v_lshlrev_b32_e32 v20, 16, v60
	v_and_b32_e32 v21, 0xffff0000, v60
	v_lshlrev_b32_e32 v22, 16, v61
	v_and_b32_e32 v23, 0xffff0000, v61
	v_mul_f32_e32 v24, 0x3fb8aa3b, v20
	v_mul_f32_e32 v25, 0x3fb8aa3b, v21
	v_pk_add_f32 v[10:11], v[10:11], v[38:39]
	v_pk_fma_f32 v[8:9], v[8:9], v[42:43], v[40:41]
	v_lshl_add_u64 v[18:19], v[18:19], 0, s[0:1]
	v_lshl_add_u64 v[18:19], v[18:19], 0, s[0:1]
	v_lshl_add_u64 v[16:17], v[16:17], 0, s[0:1]
	v_lshl_add_u64 v[16:17], v[16:17], 0, s[0:1]
	global_load_dword v44, v[18:19], off offset:-4096
	global_load_dword v45, v[16:17], off offset:-4096
	v_exp_f32_e32 v24, v24
	v_exp_f32_e32 v25, v25
	s_waitcnt vmcnt(46)
	v_lshlrev_b32_e32 v26, 16, v62
	v_and_b32_e32 v27, 0xffff0000, v62
	v_lshlrev_b32_e32 v28, 16, v63
	v_and_b32_e32 v29, 0xffff0000, v63
	v_mul_f32_e32 v30, 0x3fb8aa3b, v26
	v_mul_f32_e32 v31, 0x3fb8aa3b, v27
	v_pk_add_f32 v[10:11], v[10:11], v[20:21]
	v_pk_fma_f32 v[8:9], v[8:9], v[24:25], v[22:23]
	global_load_dword v46, v[18:19], off offset:-3840
	global_load_dword v47, v[16:17], off offset:-3840
	v_exp_f32_e32 v30, v30
	v_exp_f32_e32 v31, v31
	s_waitcnt vmcnt(46)
	v_lshlrev_b32_e32 v32, 16, v64
	v_and_b32_e32 v33, 0xffff0000, v64
	v_lshlrev_b32_e32 v34, 16, v65
	v_and_b32_e32 v35, 0xffff0000, v65
	v_mul_f32_e32 v36, 0x3fb8aa3b, v32
	v_mul_f32_e32 v37, 0x3fb8aa3b, v33
	v_pk_add_f32 v[10:11], v[10:11], v[26:27]
	v_pk_fma_f32 v[8:9], v[8:9], v[30:31], v[28:29]
	global_load_dword v48, v[18:19], off offset:-3584
	global_load_dword v49, v[16:17], off offset:-3584
	v_exp_f32_e32 v36, v36
	v_exp_f32_e32 v37, v37
	s_waitcnt vmcnt(46)
	v_lshlrev_b32_e32 v38, 16, v66
	v_and_b32_e32 v39, 0xffff0000, v66
	v_lshlrev_b32_e32 v40, 16, v67
	v_and_b32_e32 v41, 0xffff0000, v67
	v_mul_f32_e32 v42, 0x3fb8aa3b, v38
	v_mul_f32_e32 v43, 0x3fb8aa3b, v39
	v_pk_add_f32 v[10:11], v[10:11], v[32:33]
	v_pk_fma_f32 v[8:9], v[8:9], v[36:37], v[34:35]
	global_load_dword v50, v[18:19], off offset:-3328
	global_load_dword v51, v[16:17], off offset:-3328
	v_exp_f32_e32 v42, v42
	v_exp_f32_e32 v43, v43
	s_waitcnt vmcnt(46)
	v_lshlrev_b32_e32 v20, 16, v68
	v_and_b32_e32 v21, 0xffff0000, v68
	v_lshlrev_b32_e32 v22, 16, v69
	v_and_b32_e32 v23, 0xffff0000, v69
	v_mul_f32_e32 v24, 0x3fb8aa3b, v20
	v_mul_f32_e32 v25, 0x3fb8aa3b, v21
	v_pk_add_f32 v[10:11], v[10:11], v[38:39]
	v_pk_fma_f32 v[8:9], v[8:9], v[42:43], v[40:41]
	global_load_dword v52, v[18:19], off offset:-3072
	global_load_dword v53, v[16:17], off offset:-3072
	v_exp_f32_e32 v24, v24
	v_exp_f32_e32 v25, v25
	s_waitcnt vmcnt(46)
	v_lshlrev_b32_e32 v26, 16, v70
	v_and_b32_e32 v27, 0xffff0000, v70
	v_lshlrev_b32_e32 v28, 16, v71
	v_and_b32_e32 v29, 0xffff0000, v71
	v_mul_f32_e32 v30, 0x3fb8aa3b, v26
	v_mul_f32_e32 v31, 0x3fb8aa3b, v27
	v_pk_add_f32 v[10:11], v[10:11], v[20:21]
	v_pk_fma_f32 v[8:9], v[8:9], v[24:25], v[22:23]
	global_load_dword v54, v[18:19], off offset:-2816
	global_load_dword v55, v[16:17], off offset:-2816
	v_exp_f32_e32 v30, v30
	v_exp_f32_e32 v31, v31
	s_waitcnt vmcnt(46)
	v_lshlrev_b32_e32 v32, 16, v72
	v_and_b32_e32 v33, 0xffff0000, v72
	v_lshlrev_b32_e32 v34, 16, v73
	v_and_b32_e32 v35, 0xffff0000, v73
	v_mul_f32_e32 v36, 0x3fb8aa3b, v32
	v_mul_f32_e32 v37, 0x3fb8aa3b, v33
	v_pk_add_f32 v[10:11], v[10:11], v[26:27]
	v_pk_fma_f32 v[8:9], v[8:9], v[30:31], v[28:29]
	global_load_dword v56, v[18:19], off offset:-2560
	global_load_dword v57, v[16:17], off offset:-2560
	v_exp_f32_e32 v36, v36
	v_exp_f32_e32 v37, v37
	s_waitcnt vmcnt(46)
	v_lshlrev_b32_e32 v38, 16, v74
	v_and_b32_e32 v39, 0xffff0000, v74
	v_lshlrev_b32_e32 v40, 16, v75
	v_and_b32_e32 v41, 0xffff0000, v75
	v_mul_f32_e32 v42, 0x3fb8aa3b, v38
	v_mul_f32_e32 v43, 0x3fb8aa3b, v39
	v_pk_add_f32 v[10:11], v[10:11], v[32:33]
	v_pk_fma_f32 v[8:9], v[8:9], v[36:37], v[34:35]
	global_load_dword v58, v[18:19], off offset:-2304
	global_load_dword v59, v[16:17], off offset:-2304
	v_exp_f32_e32 v42, v42
	v_exp_f32_e32 v43, v43
	s_waitcnt vmcnt(46)
	v_lshlrev_b32_e32 v20, 16, v76
	v_and_b32_e32 v21, 0xffff0000, v76
	v_lshlrev_b32_e32 v22, 16, v77
	v_and_b32_e32 v23, 0xffff0000, v77
	v_mul_f32_e32 v24, 0x3fb8aa3b, v20
	v_mul_f32_e32 v25, 0x3fb8aa3b, v21
	v_pk_add_f32 v[10:11], v[10:11], v[38:39]
	v_pk_fma_f32 v[8:9], v[8:9], v[42:43], v[40:41]
	global_load_dword v60, v[18:19], off offset:-2048
	global_load_dword v61, v[16:17], off offset:-2048
	v_exp_f32_e32 v24, v24
	v_exp_f32_e32 v25, v25
	s_waitcnt vmcnt(46)
	v_lshlrev_b32_e32 v26, 16, v78
	v_and_b32_e32 v27, 0xffff0000, v78
	v_lshlrev_b32_e32 v28, 16, v79
	v_and_b32_e32 v29, 0xffff0000, v79
	v_mul_f32_e32 v30, 0x3fb8aa3b, v26
	v_mul_f32_e32 v31, 0x3fb8aa3b, v27
	v_pk_add_f32 v[10:11], v[10:11], v[20:21]
	v_pk_fma_f32 v[8:9], v[8:9], v[24:25], v[22:23]
	global_load_dword v62, v[18:19], off offset:-1792
	global_load_dword v63, v[16:17], off offset:-1792
	v_exp_f32_e32 v30, v30
	v_exp_f32_e32 v31, v31
	s_waitcnt vmcnt(46)
	v_lshlrev_b32_e32 v32, 16, v80
	v_and_b32_e32 v33, 0xffff0000, v80
	v_lshlrev_b32_e32 v34, 16, v81
	v_and_b32_e32 v35, 0xffff0000, v81
	v_mul_f32_e32 v36, 0x3fb8aa3b, v32
	v_mul_f32_e32 v37, 0x3fb8aa3b, v33
	v_pk_add_f32 v[10:11], v[10:11], v[26:27]
	v_pk_fma_f32 v[8:9], v[8:9], v[30:31], v[28:29]
	global_load_dword v64, v[18:19], off offset:-1536
	global_load_dword v65, v[16:17], off offset:-1536
	v_exp_f32_e32 v36, v36
	v_exp_f32_e32 v37, v37
	s_waitcnt vmcnt(46)
	v_lshlrev_b32_e32 v38, 16, v82
	v_and_b32_e32 v39, 0xffff0000, v82
	v_lshlrev_b32_e32 v40, 16, v83
	v_and_b32_e32 v41, 0xffff0000, v83
	v_mul_f32_e32 v42, 0x3fb8aa3b, v38
	v_mul_f32_e32 v43, 0x3fb8aa3b, v39
	v_pk_add_f32 v[10:11], v[10:11], v[32:33]
	v_pk_fma_f32 v[8:9], v[8:9], v[36:37], v[34:35]
	global_load_dword v66, v[18:19], off offset:-1280
	global_load_dword v67, v[16:17], off offset:-1280
	v_exp_f32_e32 v42, v42
	v_exp_f32_e32 v43, v43
	s_waitcnt vmcnt(46)
	v_lshlrev_b32_e32 v20, 16, v84
	v_and_b32_e32 v21, 0xffff0000, v84
	v_lshlrev_b32_e32 v22, 16, v85
	v_and_b32_e32 v23, 0xffff0000, v85
	v_mul_f32_e32 v24, 0x3fb8aa3b, v20
	v_mul_f32_e32 v25, 0x3fb8aa3b, v21
	v_pk_add_f32 v[10:11], v[10:11], v[38:39]
	v_pk_fma_f32 v[8:9], v[8:9], v[42:43], v[40:41]
	global_load_dword v68, v[18:19], off offset:-1024
	global_load_dword v69, v[16:17], off offset:-1024
	v_exp_f32_e32 v24, v24
	v_exp_f32_e32 v25, v25
	s_waitcnt vmcnt(46)
	v_lshlrev_b32_e32 v26, 16, v86
	v_and_b32_e32 v27, 0xffff0000, v86
	v_lshlrev_b32_e32 v28, 16, v87
	v_and_b32_e32 v29, 0xffff0000, v87
	v_mul_f32_e32 v30, 0x3fb8aa3b, v26
	v_mul_f32_e32 v31, 0x3fb8aa3b, v27
	v_pk_add_f32 v[10:11], v[10:11], v[20:21]
	v_pk_fma_f32 v[8:9], v[8:9], v[24:25], v[22:23]
	global_load_dword v70, v[18:19], off offset:-768
	global_load_dword v71, v[16:17], off offset:-768
	v_exp_f32_e32 v30, v30
	v_exp_f32_e32 v31, v31
	s_waitcnt vmcnt(46)
	v_lshlrev_b32_e32 v32, 16, v88
	v_and_b32_e32 v33, 0xffff0000, v88
	v_lshlrev_b32_e32 v34, 16, v89
	v_and_b32_e32 v35, 0xffff0000, v89
	v_mul_f32_e32 v36, 0x3fb8aa3b, v32
	v_mul_f32_e32 v37, 0x3fb8aa3b, v33
	v_pk_add_f32 v[10:11], v[10:11], v[26:27]
	v_pk_fma_f32 v[8:9], v[8:9], v[30:31], v[28:29]
	global_load_dword v72, v[18:19], off offset:-512
	global_load_dword v73, v[16:17], off offset:-512
	v_exp_f32_e32 v36, v36
	v_exp_f32_e32 v37, v37
	s_waitcnt vmcnt(46)
	v_lshlrev_b32_e32 v38, 16, v90
	v_and_b32_e32 v39, 0xffff0000, v90
	v_lshlrev_b32_e32 v40, 16, v91
	v_and_b32_e32 v41, 0xffff0000, v91
	v_mul_f32_e32 v42, 0x3fb8aa3b, v38
	v_mul_f32_e32 v43, 0x3fb8aa3b, v39
	v_pk_add_f32 v[10:11], v[10:11], v[32:33]
	v_pk_fma_f32 v[8:9], v[8:9], v[36:37], v[34:35]
	global_load_dword v74, v[18:19], off offset:-256
	global_load_dword v75, v[16:17], off offset:-256
	v_exp_f32_e32 v42, v42
	v_exp_f32_e32 v43, v43
	s_waitcnt vmcnt(46)
	v_lshlrev_b32_e32 v20, 16, v92
	v_and_b32_e32 v21, 0xffff0000, v92
	v_lshlrev_b32_e32 v22, 16, v93
	v_and_b32_e32 v23, 0xffff0000, v93
	v_mul_f32_e32 v24, 0x3fb8aa3b, v20
	v_mul_f32_e32 v25, 0x3fb8aa3b, v21
	v_pk_add_f32 v[10:11], v[10:11], v[38:39]
	v_pk_fma_f32 v[8:9], v[8:9], v[42:43], v[40:41]
	global_load_dword v76, v[18:19], off
	global_load_dword v77, v[16:17], off
	v_exp_f32_e32 v24, v24
	v_exp_f32_e32 v25, v25
	s_waitcnt vmcnt(46)
	v_lshlrev_b32_e32 v26, 16, v94
	v_and_b32_e32 v27, 0xffff0000, v94
	v_lshlrev_b32_e32 v28, 16, v95
	v_and_b32_e32 v29, 0xffff0000, v95
	v_mul_f32_e32 v30, 0x3fb8aa3b, v26
	v_mul_f32_e32 v31, 0x3fb8aa3b, v27
	v_pk_add_f32 v[10:11], v[10:11], v[20:21]
	v_pk_fma_f32 v[8:9], v[8:9], v[24:25], v[22:23]
	global_load_dword v78, v[18:19], off offset:256
	global_load_dword v79, v[16:17], off offset:256
	v_exp_f32_e32 v30, v30
	v_exp_f32_e32 v31, v31
	s_waitcnt vmcnt(46)
	v_lshlrev_b32_e32 v32, 16, v96
	v_and_b32_e32 v33, 0xffff0000, v96
	v_lshlrev_b32_e32 v34, 16, v97
	v_and_b32_e32 v35, 0xffff0000, v97
	v_mul_f32_e32 v36, 0x3fb8aa3b, v32
	v_mul_f32_e32 v37, 0x3fb8aa3b, v33
	v_pk_add_f32 v[10:11], v[10:11], v[26:27]
	v_pk_fma_f32 v[8:9], v[8:9], v[30:31], v[28:29]
	global_load_dword v80, v[18:19], off offset:512
	global_load_dword v81, v[16:17], off offset:512
	v_exp_f32_e32 v36, v36
	v_exp_f32_e32 v37, v37
	s_waitcnt vmcnt(46)
	v_lshlrev_b32_e32 v38, 16, v98
	v_and_b32_e32 v39, 0xffff0000, v98
	v_lshlrev_b32_e32 v40, 16, v99
	v_and_b32_e32 v41, 0xffff0000, v99
	v_mul_f32_e32 v42, 0x3fb8aa3b, v38
	v_mul_f32_e32 v43, 0x3fb8aa3b, v39
	v_pk_add_f32 v[10:11], v[10:11], v[32:33]
	v_pk_fma_f32 v[8:9], v[8:9], v[36:37], v[34:35]
	global_load_dword v82, v[18:19], off offset:768
	global_load_dword v83, v[16:17], off offset:768
	v_exp_f32_e32 v42, v42
	v_exp_f32_e32 v43, v43
	s_waitcnt vmcnt(46)
	v_lshlrev_b32_e32 v20, 16, v100
	v_and_b32_e32 v21, 0xffff0000, v100
	v_lshlrev_b32_e32 v22, 16, v101
	v_and_b32_e32 v23, 0xffff0000, v101
	v_mul_f32_e32 v24, 0x3fb8aa3b, v20
	v_mul_f32_e32 v25, 0x3fb8aa3b, v21
	v_pk_add_f32 v[10:11], v[10:11], v[38:39]
	v_pk_fma_f32 v[8:9], v[8:9], v[42:43], v[40:41]
	global_load_dword v84, v[18:19], off offset:1024
	global_load_dword v85, v[16:17], off offset:1024
	v_exp_f32_e32 v24, v24
	v_exp_f32_e32 v25, v25
	s_waitcnt vmcnt(46)
	v_lshlrev_b32_e32 v26, 16, v102
	v_and_b32_e32 v27, 0xffff0000, v102
	v_lshlrev_b32_e32 v28, 16, v103
	v_and_b32_e32 v29, 0xffff0000, v103
	v_mul_f32_e32 v30, 0x3fb8aa3b, v26
	v_mul_f32_e32 v31, 0x3fb8aa3b, v27
	v_pk_add_f32 v[10:11], v[10:11], v[20:21]
	v_pk_fma_f32 v[8:9], v[8:9], v[24:25], v[22:23]
	global_load_dword v86, v[18:19], off offset:1280
	global_load_dword v87, v[16:17], off offset:1280
	v_exp_f32_e32 v30, v30
	v_exp_f32_e32 v31, v31
	s_waitcnt vmcnt(46)
	v_lshlrev_b32_e32 v32, 16, v104
	v_and_b32_e32 v33, 0xffff0000, v104
	v_lshlrev_b32_e32 v34, 16, v105
	v_and_b32_e32 v35, 0xffff0000, v105
	v_mul_f32_e32 v36, 0x3fb8aa3b, v32
	v_mul_f32_e32 v37, 0x3fb8aa3b, v33
	v_pk_add_f32 v[10:11], v[10:11], v[26:27]
	v_pk_fma_f32 v[8:9], v[8:9], v[30:31], v[28:29]
	global_load_dword v88, v[18:19], off offset:1536
	global_load_dword v89, v[16:17], off offset:1536
	v_exp_f32_e32 v36, v36
	v_exp_f32_e32 v37, v37
	s_waitcnt vmcnt(46)
	v_lshlrev_b32_e32 v38, 16, v106
	v_and_b32_e32 v39, 0xffff0000, v106
	v_lshlrev_b32_e32 v40, 16, v107
	v_and_b32_e32 v41, 0xffff0000, v107
	v_mul_f32_e32 v42, 0x3fb8aa3b, v38
	v_mul_f32_e32 v43, 0x3fb8aa3b, v39
	v_pk_add_f32 v[10:11], v[10:11], v[32:33]
	v_pk_fma_f32 v[8:9], v[8:9], v[36:37], v[34:35]
	global_load_dword v90, v[18:19], off offset:1792
	global_load_dword v91, v[16:17], off offset:1792
	v_exp_f32_e32 v42, v42
	v_exp_f32_e32 v43, v43
	s_waitcnt vmcnt(46)
	v_lshlrev_b32_e32 v20, 16, v44
	v_and_b32_e32 v21, 0xffff0000, v44
	v_lshlrev_b32_e32 v22, 16, v45
	v_and_b32_e32 v23, 0xffff0000, v45
	v_mul_f32_e32 v24, 0x3fb8aa3b, v20
	v_mul_f32_e32 v25, 0x3fb8aa3b, v21
	v_pk_add_f32 v[10:11], v[10:11], v[38:39]
	v_pk_fma_f32 v[8:9], v[8:9], v[42:43], v[40:41]
	global_load_dword v92, v[18:19], off offset:2048
	global_load_dword v93, v[16:17], off offset:2048
	v_exp_f32_e32 v24, v24
	v_exp_f32_e32 v25, v25
	s_waitcnt vmcnt(46)
	v_lshlrev_b32_e32 v26, 16, v46
	v_and_b32_e32 v27, 0xffff0000, v46
	v_lshlrev_b32_e32 v28, 16, v47
	v_and_b32_e32 v29, 0xffff0000, v47
	v_mul_f32_e32 v30, 0x3fb8aa3b, v26
	v_mul_f32_e32 v31, 0x3fb8aa3b, v27
	v_pk_add_f32 v[10:11], v[10:11], v[20:21]
	v_pk_fma_f32 v[8:9], v[8:9], v[24:25], v[22:23]
	global_load_dword v94, v[18:19], off offset:2304
	global_load_dword v95, v[16:17], off offset:2304
	v_exp_f32_e32 v30, v30
	v_exp_f32_e32 v31, v31
	s_waitcnt vmcnt(46)
	v_lshlrev_b32_e32 v32, 16, v48
	v_and_b32_e32 v33, 0xffff0000, v48
	v_lshlrev_b32_e32 v34, 16, v49
	v_and_b32_e32 v35, 0xffff0000, v49
	v_mul_f32_e32 v36, 0x3fb8aa3b, v32
	v_mul_f32_e32 v37, 0x3fb8aa3b, v33
	v_pk_add_f32 v[10:11], v[10:11], v[26:27]
	v_pk_fma_f32 v[8:9], v[8:9], v[30:31], v[28:29]
	global_load_dword v96, v[18:19], off offset:2560
	global_load_dword v97, v[16:17], off offset:2560
	v_exp_f32_e32 v36, v36
	v_exp_f32_e32 v37, v37
	s_waitcnt vmcnt(46)
	v_lshlrev_b32_e32 v38, 16, v50
	v_and_b32_e32 v39, 0xffff0000, v50
	v_lshlrev_b32_e32 v40, 16, v51
	v_and_b32_e32 v41, 0xffff0000, v51
	v_mul_f32_e32 v42, 0x3fb8aa3b, v38
	v_mul_f32_e32 v43, 0x3fb8aa3b, v39
	v_pk_add_f32 v[10:11], v[10:11], v[32:33]
	v_pk_fma_f32 v[8:9], v[8:9], v[36:37], v[34:35]
	global_load_dword v98, v[18:19], off offset:2816
	global_load_dword v99, v[16:17], off offset:2816
	v_exp_f32_e32 v42, v42
	v_exp_f32_e32 v43, v43
	s_waitcnt vmcnt(46)
	v_lshlrev_b32_e32 v20, 16, v52
	v_and_b32_e32 v21, 0xffff0000, v52
	v_lshlrev_b32_e32 v22, 16, v53
	v_and_b32_e32 v23, 0xffff0000, v53
	v_mul_f32_e32 v24, 0x3fb8aa3b, v20
	v_mul_f32_e32 v25, 0x3fb8aa3b, v21
	v_pk_add_f32 v[10:11], v[10:11], v[38:39]
	v_pk_fma_f32 v[8:9], v[8:9], v[42:43], v[40:41]
	global_load_dword v100, v[18:19], off offset:3072
	global_load_dword v101, v[16:17], off offset:3072
	v_exp_f32_e32 v24, v24
	v_exp_f32_e32 v25, v25
	s_waitcnt vmcnt(46)
	v_lshlrev_b32_e32 v26, 16, v54
	v_and_b32_e32 v27, 0xffff0000, v54
	v_lshlrev_b32_e32 v28, 16, v55
	v_and_b32_e32 v29, 0xffff0000, v55
	v_mul_f32_e32 v30, 0x3fb8aa3b, v26
	v_mul_f32_e32 v31, 0x3fb8aa3b, v27
	v_pk_add_f32 v[10:11], v[10:11], v[20:21]
	v_pk_fma_f32 v[8:9], v[8:9], v[24:25], v[22:23]
	global_load_dword v102, v[18:19], off offset:3328
	global_load_dword v103, v[16:17], off offset:3328
	v_exp_f32_e32 v30, v30
	v_exp_f32_e32 v31, v31
	s_waitcnt vmcnt(46)
	v_lshlrev_b32_e32 v32, 16, v56
	v_and_b32_e32 v33, 0xffff0000, v56
	v_lshlrev_b32_e32 v34, 16, v57
	v_and_b32_e32 v35, 0xffff0000, v57
	v_mul_f32_e32 v36, 0x3fb8aa3b, v32
	v_mul_f32_e32 v37, 0x3fb8aa3b, v33
	v_pk_add_f32 v[10:11], v[10:11], v[26:27]
	v_pk_fma_f32 v[8:9], v[8:9], v[30:31], v[28:29]
	global_load_dword v104, v[18:19], off offset:3584
	global_load_dword v105, v[16:17], off offset:3584
	v_exp_f32_e32 v36, v36
	v_exp_f32_e32 v37, v37
	s_waitcnt vmcnt(46)
	v_lshlrev_b32_e32 v38, 16, v58
	v_and_b32_e32 v39, 0xffff0000, v58
	v_lshlrev_b32_e32 v40, 16, v59
	v_and_b32_e32 v41, 0xffff0000, v59
	v_mul_f32_e32 v42, 0x3fb8aa3b, v38
	v_mul_f32_e32 v43, 0x3fb8aa3b, v39
	v_pk_add_f32 v[10:11], v[10:11], v[32:33]
	v_pk_fma_f32 v[8:9], v[8:9], v[36:37], v[34:35]
	global_load_dword v106, v[18:19], off offset:3840
	global_load_dword v107, v[16:17], off offset:3840
	v_exp_f32_e32 v42, v42
	v_exp_f32_e32 v43, v43
	s_waitcnt vmcnt(46)
	v_lshlrev_b32_e32 v20, 16, v60
	v_and_b32_e32 v21, 0xffff0000, v60
	v_lshlrev_b32_e32 v22, 16, v61
	v_and_b32_e32 v23, 0xffff0000, v61
	v_mul_f32_e32 v24, 0x3fb8aa3b, v20
	v_mul_f32_e32 v25, 0x3fb8aa3b, v21
	v_pk_add_f32 v[10:11], v[10:11], v[38:39]
	v_pk_fma_f32 v[8:9], v[8:9], v[42:43], v[40:41]
	v_exp_f32_e32 v24, v24
	v_exp_f32_e32 v25, v25
	s_waitcnt vmcnt(44)
	v_lshlrev_b32_e32 v26, 16, v62
	v_and_b32_e32 v27, 0xffff0000, v62
	v_lshlrev_b32_e32 v28, 16, v63
	v_and_b32_e32 v29, 0xffff0000, v63
	v_mul_f32_e32 v30, 0x3fb8aa3b, v26
	v_mul_f32_e32 v31, 0x3fb8aa3b, v27
	v_pk_add_f32 v[10:11], v[10:11], v[20:21]
	v_pk_fma_f32 v[8:9], v[8:9], v[24:25], v[22:23]
	v_exp_f32_e32 v30, v30
	v_exp_f32_e32 v31, v31
	s_waitcnt vmcnt(42)
	v_lshlrev_b32_e32 v32, 16, v64
	v_and_b32_e32 v33, 0xffff0000, v64
	v_lshlrev_b32_e32 v34, 16, v65
	v_and_b32_e32 v35, 0xffff0000, v65
	v_mul_f32_e32 v36, 0x3fb8aa3b, v32
	v_mul_f32_e32 v37, 0x3fb8aa3b, v33
	v_pk_add_f32 v[10:11], v[10:11], v[26:27]
	v_pk_fma_f32 v[8:9], v[8:9], v[30:31], v[28:29]
	v_exp_f32_e32 v36, v36
	v_exp_f32_e32 v37, v37
	s_waitcnt vmcnt(40)
	v_lshlrev_b32_e32 v38, 16, v66
	v_and_b32_e32 v39, 0xffff0000, v66
	v_lshlrev_b32_e32 v40, 16, v67
	v_and_b32_e32 v41, 0xffff0000, v67
	v_mul_f32_e32 v42, 0x3fb8aa3b, v38
	v_mul_f32_e32 v43, 0x3fb8aa3b, v39
	v_pk_add_f32 v[10:11], v[10:11], v[32:33]
	v_pk_fma_f32 v[8:9], v[8:9], v[36:37], v[34:35]
	v_exp_f32_e32 v42, v42
	v_exp_f32_e32 v43, v43
	s_waitcnt vmcnt(38)
	v_lshlrev_b32_e32 v20, 16, v68
	v_and_b32_e32 v21, 0xffff0000, v68
	v_lshlrev_b32_e32 v22, 16, v69
	v_and_b32_e32 v23, 0xffff0000, v69
	v_mul_f32_e32 v24, 0x3fb8aa3b, v20
	v_mul_f32_e32 v25, 0x3fb8aa3b, v21
	v_pk_add_f32 v[10:11], v[10:11], v[38:39]
	v_pk_fma_f32 v[8:9], v[8:9], v[42:43], v[40:41]
	v_exp_f32_e32 v24, v24
	v_exp_f32_e32 v25, v25
	s_waitcnt vmcnt(36)
	v_lshlrev_b32_e32 v26, 16, v70
	v_and_b32_e32 v27, 0xffff0000, v70
	v_lshlrev_b32_e32 v28, 16, v71
	v_and_b32_e32 v29, 0xffff0000, v71
	v_mul_f32_e32 v30, 0x3fb8aa3b, v26
	v_mul_f32_e32 v31, 0x3fb8aa3b, v27
	v_pk_add_f32 v[10:11], v[10:11], v[20:21]
	v_pk_fma_f32 v[8:9], v[8:9], v[24:25], v[22:23]
	v_exp_f32_e32 v30, v30
	v_exp_f32_e32 v31, v31
	s_waitcnt vmcnt(34)
	v_lshlrev_b32_e32 v32, 16, v72
	v_and_b32_e32 v33, 0xffff0000, v72
	v_lshlrev_b32_e32 v34, 16, v73
	v_and_b32_e32 v35, 0xffff0000, v73
	v_mul_f32_e32 v36, 0x3fb8aa3b, v32
	v_mul_f32_e32 v37, 0x3fb8aa3b, v33
	v_pk_add_f32 v[10:11], v[10:11], v[26:27]
	v_pk_fma_f32 v[8:9], v[8:9], v[30:31], v[28:29]
	v_exp_f32_e32 v36, v36
	v_exp_f32_e32 v37, v37
	s_waitcnt vmcnt(32)
	v_lshlrev_b32_e32 v38, 16, v74
	v_and_b32_e32 v39, 0xffff0000, v74
	v_lshlrev_b32_e32 v40, 16, v75
	v_and_b32_e32 v41, 0xffff0000, v75
	v_mul_f32_e32 v42, 0x3fb8aa3b, v38
	v_mul_f32_e32 v43, 0x3fb8aa3b, v39
	v_pk_add_f32 v[10:11], v[10:11], v[32:33]
	v_pk_fma_f32 v[8:9], v[8:9], v[36:37], v[34:35]
	v_exp_f32_e32 v42, v42
	v_exp_f32_e32 v43, v43
	s_waitcnt vmcnt(30)
	v_lshlrev_b32_e32 v20, 16, v76
	v_and_b32_e32 v21, 0xffff0000, v76
	v_lshlrev_b32_e32 v22, 16, v77
	v_and_b32_e32 v23, 0xffff0000, v77
	v_mul_f32_e32 v24, 0x3fb8aa3b, v20
	v_mul_f32_e32 v25, 0x3fb8aa3b, v21
	v_pk_add_f32 v[10:11], v[10:11], v[38:39]
	v_pk_fma_f32 v[8:9], v[8:9], v[42:43], v[40:41]
	v_exp_f32_e32 v24, v24
	v_exp_f32_e32 v25, v25
	s_waitcnt vmcnt(28)
	v_lshlrev_b32_e32 v26, 16, v78
	v_and_b32_e32 v27, 0xffff0000, v78
	v_lshlrev_b32_e32 v28, 16, v79
	v_and_b32_e32 v29, 0xffff0000, v79
	v_mul_f32_e32 v30, 0x3fb8aa3b, v26
	v_mul_f32_e32 v31, 0x3fb8aa3b, v27
	v_pk_add_f32 v[10:11], v[10:11], v[20:21]
	v_pk_fma_f32 v[8:9], v[8:9], v[24:25], v[22:23]
	v_exp_f32_e32 v30, v30
	v_exp_f32_e32 v31, v31
	s_waitcnt vmcnt(26)
	v_lshlrev_b32_e32 v32, 16, v80
	v_and_b32_e32 v33, 0xffff0000, v80
	v_lshlrev_b32_e32 v34, 16, v81
	v_and_b32_e32 v35, 0xffff0000, v81
	v_mul_f32_e32 v36, 0x3fb8aa3b, v32
	v_mul_f32_e32 v37, 0x3fb8aa3b, v33
	v_pk_add_f32 v[10:11], v[10:11], v[26:27]
	v_pk_fma_f32 v[8:9], v[8:9], v[30:31], v[28:29]
	v_exp_f32_e32 v36, v36
	v_exp_f32_e32 v37, v37
	s_waitcnt vmcnt(24)
	v_lshlrev_b32_e32 v38, 16, v82
	v_and_b32_e32 v39, 0xffff0000, v82
	v_lshlrev_b32_e32 v40, 16, v83
	v_and_b32_e32 v41, 0xffff0000, v83
	v_mul_f32_e32 v42, 0x3fb8aa3b, v38
	v_mul_f32_e32 v43, 0x3fb8aa3b, v39
	v_pk_add_f32 v[10:11], v[10:11], v[32:33]
	v_pk_fma_f32 v[8:9], v[8:9], v[36:37], v[34:35]
	v_exp_f32_e32 v42, v42
	v_exp_f32_e32 v43, v43
	s_waitcnt vmcnt(22)
	v_lshlrev_b32_e32 v20, 16, v84
	v_and_b32_e32 v21, 0xffff0000, v84
	v_lshlrev_b32_e32 v22, 16, v85
	v_and_b32_e32 v23, 0xffff0000, v85
	v_mul_f32_e32 v24, 0x3fb8aa3b, v20
	v_mul_f32_e32 v25, 0x3fb8aa3b, v21
	v_pk_add_f32 v[10:11], v[10:11], v[38:39]
	v_pk_fma_f32 v[8:9], v[8:9], v[42:43], v[40:41]
	v_exp_f32_e32 v24, v24
	v_exp_f32_e32 v25, v25
	s_waitcnt vmcnt(20)
	v_lshlrev_b32_e32 v26, 16, v86
	v_and_b32_e32 v27, 0xffff0000, v86
	v_lshlrev_b32_e32 v28, 16, v87
	v_and_b32_e32 v29, 0xffff0000, v87
	v_mul_f32_e32 v30, 0x3fb8aa3b, v26
	v_mul_f32_e32 v31, 0x3fb8aa3b, v27
	v_pk_add_f32 v[10:11], v[10:11], v[20:21]
	v_pk_fma_f32 v[8:9], v[8:9], v[24:25], v[22:23]
	v_exp_f32_e32 v30, v30
	v_exp_f32_e32 v31, v31
	s_waitcnt vmcnt(18)
	v_lshlrev_b32_e32 v32, 16, v88
	v_and_b32_e32 v33, 0xffff0000, v88
	v_lshlrev_b32_e32 v34, 16, v89
	v_and_b32_e32 v35, 0xffff0000, v89
	v_mul_f32_e32 v36, 0x3fb8aa3b, v32
	v_mul_f32_e32 v37, 0x3fb8aa3b, v33
	v_pk_add_f32 v[10:11], v[10:11], v[26:27]
	v_pk_fma_f32 v[8:9], v[8:9], v[30:31], v[28:29]
	v_exp_f32_e32 v36, v36
	v_exp_f32_e32 v37, v37
	s_waitcnt vmcnt(16)
	v_lshlrev_b32_e32 v38, 16, v90
	v_and_b32_e32 v39, 0xffff0000, v90
	v_lshlrev_b32_e32 v40, 16, v91
	v_and_b32_e32 v41, 0xffff0000, v91
	v_mul_f32_e32 v42, 0x3fb8aa3b, v38
	v_mul_f32_e32 v43, 0x3fb8aa3b, v39
	v_pk_add_f32 v[10:11], v[10:11], v[32:33]
	v_pk_fma_f32 v[8:9], v[8:9], v[36:37], v[34:35]
	v_exp_f32_e32 v42, v42
	v_exp_f32_e32 v43, v43
	s_waitcnt vmcnt(14)
	v_lshlrev_b32_e32 v20, 16, v92
	v_and_b32_e32 v21, 0xffff0000, v92
	v_lshlrev_b32_e32 v22, 16, v93
	v_and_b32_e32 v23, 0xffff0000, v93
	v_mul_f32_e32 v24, 0x3fb8aa3b, v20
	v_mul_f32_e32 v25, 0x3fb8aa3b, v21
	v_pk_add_f32 v[10:11], v[10:11], v[38:39]
	v_pk_fma_f32 v[8:9], v[8:9], v[42:43], v[40:41]
	v_exp_f32_e32 v24, v24
	v_exp_f32_e32 v25, v25
	s_waitcnt vmcnt(12)
	v_lshlrev_b32_e32 v26, 16, v94
	v_and_b32_e32 v27, 0xffff0000, v94
	v_lshlrev_b32_e32 v28, 16, v95
	v_and_b32_e32 v29, 0xffff0000, v95
	v_mul_f32_e32 v30, 0x3fb8aa3b, v26
	v_mul_f32_e32 v31, 0x3fb8aa3b, v27
	v_pk_add_f32 v[10:11], v[10:11], v[20:21]
	v_pk_fma_f32 v[8:9], v[8:9], v[24:25], v[22:23]
	v_exp_f32_e32 v30, v30
	v_exp_f32_e32 v31, v31
	s_waitcnt vmcnt(10)
	v_lshlrev_b32_e32 v32, 16, v96
	v_and_b32_e32 v33, 0xffff0000, v96
	v_lshlrev_b32_e32 v34, 16, v97
	v_and_b32_e32 v35, 0xffff0000, v97
	v_mul_f32_e32 v36, 0x3fb8aa3b, v32
	v_mul_f32_e32 v37, 0x3fb8aa3b, v33
	v_pk_add_f32 v[10:11], v[10:11], v[26:27]
	v_pk_fma_f32 v[8:9], v[8:9], v[30:31], v[28:29]
	v_exp_f32_e32 v36, v36
	v_exp_f32_e32 v37, v37
	s_waitcnt vmcnt(8)
	v_lshlrev_b32_e32 v38, 16, v98
	v_and_b32_e32 v39, 0xffff0000, v98
	v_lshlrev_b32_e32 v40, 16, v99
	v_and_b32_e32 v41, 0xffff0000, v99
	v_mul_f32_e32 v42, 0x3fb8aa3b, v38
	v_mul_f32_e32 v43, 0x3fb8aa3b, v39
	v_pk_add_f32 v[10:11], v[10:11], v[32:33]
	v_pk_fma_f32 v[8:9], v[8:9], v[36:37], v[34:35]
	v_exp_f32_e32 v42, v42
	v_exp_f32_e32 v43, v43
	s_waitcnt vmcnt(6)
	v_lshlrev_b32_e32 v20, 16, v100
	v_and_b32_e32 v21, 0xffff0000, v100
	v_lshlrev_b32_e32 v22, 16, v101
	v_and_b32_e32 v23, 0xffff0000, v101
	v_mul_f32_e32 v24, 0x3fb8aa3b, v20
	v_mul_f32_e32 v25, 0x3fb8aa3b, v21
	v_pk_add_f32 v[10:11], v[10:11], v[38:39]
	v_pk_fma_f32 v[8:9], v[8:9], v[42:43], v[40:41]
	v_exp_f32_e32 v24, v24
	v_exp_f32_e32 v25, v25
	s_waitcnt vmcnt(4)
	v_lshlrev_b32_e32 v26, 16, v102
	v_and_b32_e32 v27, 0xffff0000, v102
	v_lshlrev_b32_e32 v28, 16, v103
	v_and_b32_e32 v29, 0xffff0000, v103
	v_mul_f32_e32 v30, 0x3fb8aa3b, v26
	v_mul_f32_e32 v31, 0x3fb8aa3b, v27
	v_pk_add_f32 v[10:11], v[10:11], v[20:21]
	v_pk_fma_f32 v[8:9], v[8:9], v[24:25], v[22:23]
	v_exp_f32_e32 v30, v30
	v_exp_f32_e32 v31, v31
	s_waitcnt vmcnt(2)
	v_lshlrev_b32_e32 v32, 16, v104
	v_and_b32_e32 v33, 0xffff0000, v104
	v_lshlrev_b32_e32 v34, 16, v105
	v_and_b32_e32 v35, 0xffff0000, v105
	v_mul_f32_e32 v36, 0x3fb8aa3b, v32
	v_mul_f32_e32 v37, 0x3fb8aa3b, v33
	v_pk_add_f32 v[10:11], v[10:11], v[26:27]
	v_pk_fma_f32 v[8:9], v[8:9], v[30:31], v[28:29]
	v_exp_f32_e32 v36, v36
	v_exp_f32_e32 v37, v37
	s_waitcnt vmcnt(0)
	v_lshlrev_b32_e32 v38, 16, v106
	v_and_b32_e32 v39, 0xffff0000, v106
	v_lshlrev_b32_e32 v40, 16, v107
	v_and_b32_e32 v41, 0xffff0000, v107
	v_mul_f32_e32 v42, 0x3fb8aa3b, v38
	v_mul_f32_e32 v43, 0x3fb8aa3b, v39
	v_pk_add_f32 v[10:11], v[10:11], v[32:33]
	v_pk_fma_f32 v[8:9], v[8:9], v[36:37], v[34:35]
	v_exp_f32_e32 v42, v42
	v_exp_f32_e32 v43, v43
	s_nop 0
	v_pk_add_f32 v[10:11], v[10:11], v[38:39]
	v_pk_fma_f32 v[8:9], v[8:9], v[42:43], v[40:41]
	s_lshl_b32 s4, s17, 5
	s_and_b32 s4, s4, 32
	s_or_b32 s4, s6, s4
	s_add_i32 s4, s4, s8
	s_ashr_i32 s6, s4, 5
	s_lshl_b32 s4, s8, 7
	s_ashr_i32 s7, s6, 31
	s_and_b32 s4, s4, 0xf80
	s_lshl_b64 s[6:7], s[6:7], 14
	v_mul_f32_e32 v6, 0x3fb8aa3b, v10
	v_mul_f32_e32 v7, 0x3fb8aa3b, v11
	s_add_u32 s18, s14, s6
	v_exp_f32_e32 v6, v6
	v_exp_f32_e32 v7, v7
	s_addc_u32 s19, s15, s7
	v_or_b32_e32 v12, s4, v14
	s_add_u32 s6, s10, s6
	v_lshlrev_b32_e32 v10, 2, v12
	s_addc_u32 s7, s11, s7
	global_store_dwordx2 v10, v[8:9], s[6:7]
	s_add_i32 s17, s17, 8
	s_addk_i32 s16, 0x100
	s_mov_b64 s[6:7], 0
	global_store_dwordx2 v10, v[6:7], s[18:19]
	s_branch .LBB0_472
